# v2 + residual-add epilogues (P5/P9/P13): 4 base loads per row-group issued together with counted vmcnt instead of load;vmcnt(0) chains
# speedup vs baseline: 1.0200x; 1.0200x over previous
; __device__ __forceinline__ unsigned pk2(float lo, float hi) { f32x2_t v = {lo, hi}; bf16x2_t b = __builtin_convertvector(v, bf16x2_t); return __builtin_bit_cast(unsigned, b); }
;     __device__ __forceinline__ void operator()(const f32x4 (&acc)[2][2][4][2], const Unit& u, int wr, int wc, int fr, int fq) const {
;     ...
;             for (int m = 0; m < 4; ++m) { const int row = row0 + ai * HALF + m * 16;
;                 const float* bp = base + (size_t)row * D + col0; float* op = out + (size_t)row * D + col0; bf16_t* xp = xb + (size_t)row * D + col0;
;                 float ss = 0.f;
; #pragma unroll
;                 for (int bj = 0; bj < 2; ++bj)
; #pragma unroll
;                     for (int n = 0; n < 2; ++n) { const f32x4 b = *(const f32x4*)(bp + bj * HALF + n * 16); const f32x4 x = b + acc[ai][bj][m][n]; *(f32x4*)(op + bj * HALF + n * 16) = x;
;                         u32x2 w; w.x = pk2(x.x, x.y); w.y = pk2(x.z, x.w); *(u32x2*)(xp + bj * HALF + n * 16) = w; ss += (x.x * x.x + x.y * x.y) + (x.z * x.z + x.w * x.w); }
;                 ss += __shfl_xor(ss, 16); ss += __shfl_xor(ss, 32);
;                 if (fq == 0) sred[wc * 256 + ai * HALF + wr * 64 + m * 16 + fr] = ss; }
.LBB0_521:
	s_lshl_b32 s15, s52, 8
	v_add_u32_e32 v142, s15, v146
	v_lshl_or_b32 v140, s14, 8, v148
	v_ashrrev_i32_e32 v143, 31, v142
	v_ashrrev_i32_e32 v141, 31, v140
	v_lshlrev_b64 v[160:161], 13, v[142:143]
	v_lshl_add_u64 v[156:157], s[12:13], 0, v[160:161]
	v_lshlrev_b64 v[144:145], 2, v[140:141]
	v_lshl_add_u64 v[162:163], v[156:157], 0, v[144:145]
	global_load_dwordx4 v[234:237], v[162:163], off
	global_load_dwordx4 v[238:241], v[162:163], off offset:64
	global_load_dwordx4 v[242:245], v[162:163], off offset:512
	global_load_dwordx4 v[246:249], v[162:163], off offset:576
	v_lshlrev_b64 v[164:165], 12, v[142:143]
	v_lshl_add_u64 v[160:161], s[20:21], 0, v[160:161]
	v_lshl_add_u64 v[164:165], s[22:23], 0, v[164:165]
	v_lshl_add_u64 v[166:167], v[160:161], 0, v[144:145]
	v_lshl_add_u64 v[164:165], v[140:141], 1, v[164:165]
	s_waitcnt vmcnt(3)
	v_pk_add_f32 v[126:127], v[126:127], v[236:237]
	v_pk_add_f32 v[124:125], v[124:125], v[234:235]
	v_cvt_pk_bf16_f32 v157, v126, v127
	v_cvt_pk_bf16_f32 v156, v124, v125
	global_store_dwordx4 v[166:167], v[124:127], off
	global_store_dwordx2 v[164:165], v[156:157], off
	s_waitcnt vmcnt(4)
	v_pk_add_f32 v[122:123], v[122:123], v[240:241]
	v_pk_add_f32 v[120:121], v[120:121], v[238:239]
	v_cvt_pk_bf16_f32 v157, v122, v123
	v_cvt_pk_bf16_f32 v156, v120, v121
	global_store_dwordx4 v[166:167], v[120:123], off offset:64
	global_store_dwordx2 v[164:165], v[156:157], off offset:32
	s_waitcnt vmcnt(5)
	v_pk_add_f32 v[158:159], v[118:119], v[244:245]
	v_pk_add_f32 v[156:157], v[116:117], v[242:243]
	v_cvt_pk_bf16_f32 v117, v158, v159
	v_cvt_pk_bf16_f32 v116, v156, v157
	global_store_dwordx4 v[166:167], v[156:159], off offset:512
	global_store_dwordx2 v[164:165], v[116:117], off offset:256
	v_mul_f32_e32 v118, v125, v125
	v_mul_f32_e32 v119, v127, v127
	v_fmac_f32_e32 v118, v124, v124
	v_fmac_f32_e32 v119, v126, v126
	v_add_f32_e32 v118, v118, v119
	v_mul_f32_e32 v119, v121, v121
	v_mul_f32_e32 v121, v123, v123
	v_fmac_f32_e32 v119, v120, v120
	v_fmac_f32_e32 v121, v122, v122
	v_add_f32_e32 v119, v119, v121
	v_add_f32_e32 v118, v118, v119
	v_mul_f32_e32 v119, v157, v157
	v_mul_f32_e32 v120, v159, v159
	v_fmac_f32_e32 v119, v156, v156
	v_fmac_f32_e32 v120, v158, v158
	v_add_f32_e32 v119, v119, v120
	v_and_b32_e32 v117, 64, v154
	v_add_f32_e32 v122, v118, v119
	v_xor_b32_e32 v116, 16, v154
	v_add_u32_e32 v117, 64, v117
	v_cmp_lt_i32_e32 vcc, v116, v117
	s_waitcnt vmcnt(6)
	v_pk_add_f32 v[120:121], v[114:115], v[248:249]
	v_pk_add_f32 v[118:119], v[112:113], v[246:247]
	v_mul_f32_e32 v113, v121, v121
	v_mul_f32_e32 v112, v119, v119
	v_fmac_f32_e32 v112, v118, v118
	v_fmac_f32_e32 v113, v120, v120
	v_cndmask_b32_e32 v116, v154, v116, vcc
	v_add_f32_e32 v112, v112, v113
	v_lshlrev_b32_e32 v116, 2, v116
	v_add_f32_e32 v113, v122, v112
	ds_bpermute_b32 v114, v116, v113
	v_xor_b32_e32 v112, 32, v154
	v_cmp_lt_i32_e32 vcc, v112, v117
	global_store_dwordx4 v[166:167], v[118:121], off offset:576
	s_waitcnt lgkmcnt(0)
	v_add_f32_e32 v113, v113, v114
	v_cndmask_b32_e32 v112, v154, v112, vcc
	v_lshlrev_b32_e32 v112, 2, v112
	ds_bpermute_b32 v114, v112, v113
	v_cvt_pk_bf16_f32 v118, v118, v119
	v_cvt_pk_bf16_f32 v119, v120, v121
	global_store_dwordx2 v[164:165], v[118:119], off offset:288
	s_and_saveexec_b64 s[52:53], s[4:5]
	s_cbranch_execz .LBB0_523
	s_waitcnt lgkmcnt(0)
	v_add_f32_e32 v113, v113, v114
	ds_write_b32 v149, v113
.LBB0_523:
	s_or_b64 exec, exec, s[52:53]
	s_waitcnt lgkmcnt(0)
	v_or_b32_e32 v114, 16, v142
	v_ashrrev_i32_e32 v115, 31, v114
	v_lshlrev_b64 v[122:123], 13, v[114:115]
	v_lshl_add_u64 v[118:119], s[12:13], 0, v[122:123]
	v_lshl_add_u64 v[124:125], v[118:119], 0, v[144:145]
	global_load_dwordx4 v[234:237], v[124:125], off
	global_load_dwordx4 v[238:241], v[124:125], off offset:64
	global_load_dwordx4 v[242:245], v[124:125], off offset:512
	global_load_dwordx4 v[246:249], v[124:125], off offset:576
	v_lshlrev_b64 v[114:115], 12, v[114:115]
	v_lshl_add_u64 v[122:123], s[20:21], 0, v[122:123]
	v_lshl_add_u64 v[114:115], s[22:23], 0, v[114:115]
	v_lshl_add_u64 v[122:123], v[122:123], 0, v[144:145]
	v_lshl_add_u64 v[114:115], v[140:141], 1, v[114:115]
	s_waitcnt vmcnt(3)
	v_pk_add_f32 v[110:111], v[110:111], v[236:237]
	v_pk_add_f32 v[108:109], v[108:109], v[234:235]
	v_cvt_pk_bf16_f32 v119, v110, v111
	v_cvt_pk_bf16_f32 v118, v108, v109
	global_store_dwordx4 v[122:123], v[108:111], off
	global_store_dwordx2 v[114:115], v[118:119], off
	s_nop 0
	v_mul_f32_e32 v109, v109, v109
	v_mul_f32_e32 v111, v111, v111
	v_fmac_f32_e32 v109, v108, v108
	v_fmac_f32_e32 v111, v110, v110
	v_add_f32_e32 v108, v109, v111
	s_waitcnt vmcnt(4)
	v_pk_add_f32 v[106:107], v[106:107], v[240:241]
	v_pk_add_f32 v[104:105], v[104:105], v[238:239]
	v_cvt_pk_bf16_f32 v119, v106, v107
	v_cvt_pk_bf16_f32 v118, v104, v105
	global_store_dwordx4 v[122:123], v[104:107], off offset:64
	global_store_dwordx2 v[114:115], v[118:119], off offset:32
	s_nop 0
	v_mul_f32_e32 v105, v105, v105
	v_mul_f32_e32 v107, v107, v107
	v_fmac_f32_e32 v105, v104, v104
	v_fmac_f32_e32 v107, v106, v106
	v_add_f32_e32 v104, v105, v107
	v_add_f32_e32 v104, v108, v104
	s_waitcnt vmcnt(5)
	v_pk_add_f32 v[102:103], v[102:103], v[244:245]
	v_pk_add_f32 v[100:101], v[100:101], v[242:243]
	v_cvt_pk_bf16_f32 v119, v102, v103
	v_cvt_pk_bf16_f32 v118, v100, v101
	global_store_dwordx4 v[122:123], v[100:103], off offset:512
	global_store_dwordx2 v[114:115], v[118:119], off offset:256
	s_nop 0
	v_mul_f32_e32 v101, v101, v101
	v_mul_f32_e32 v103, v103, v103
	v_fmac_f32_e32 v101, v100, v100
	v_fmac_f32_e32 v103, v102, v102
	v_add_f32_e32 v100, v101, v103
	v_add_f32_e32 v102, v104, v100
	s_waitcnt vmcnt(6)
	v_pk_add_f32 v[100:101], v[98:99], v[248:249]
	v_pk_add_f32 v[98:99], v[96:97], v[246:247]
	v_mul_f32_e32 v97, v101, v101
	v_mul_f32_e32 v96, v99, v99
	v_fmac_f32_e32 v96, v98, v98
	v_fmac_f32_e32 v97, v100, v100
	v_add_f32_e32 v96, v96, v97
	v_add_f32_e32 v96, v102, v96
	ds_bpermute_b32 v97, v116, v96
	global_store_dwordx4 v[122:123], v[98:101], off offset:576
	s_waitcnt lgkmcnt(0)
	v_add_f32_e32 v96, v96, v97
	ds_bpermute_b32 v97, v112, v96
	v_cvt_pk_bf16_f32 v98, v98, v99
	v_cvt_pk_bf16_f32 v99, v100, v101
	global_store_dwordx2 v[114:115], v[98:99], off offset:288
	s_and_saveexec_b64 s[52:53], s[4:5]
	s_cbranch_execz .LBB0_525
	s_waitcnt lgkmcnt(0)
	v_add_f32_e32 v96, v96, v97
	ds_write_b32 v149, v96 offset:64
; __device__ __forceinline__ unsigned pk2(float lo, float hi) { f32x2_t v = {lo, hi}; bf16x2_t b = __builtin_convertvector(v, bf16x2_t); return __builtin_bit_cast(unsigned, b); }
;     __device__ __forceinline__ void operator()(const f32x4 (&acc)[2][2][4][2], const Unit& u, int wr, int wc, int fr, int fq) const {
;     ...
;             for (int m = 0; m < 4; ++m) { const int row = row0 + ai * HALF + m * 16;
;                 const float* bp = base + (size_t)row * D + col0; float* op = out + (size_t)row * D + col0; bf16_t* xp = xb + (size_t)row * D + col0;
;                 float ss = 0.f;
; #pragma unroll
;                 for (int bj = 0; bj < 2; ++bj)
; #pragma unroll
;                     for (int n = 0; n < 2; ++n) { const f32x4 b = *(const f32x4*)(bp + bj * HALF + n * 16); const f32x4 x = b + acc[ai][bj][m][n]; *(f32x4*)(op + bj * HALF + n * 16) = x;
;                         u32x2 w; w.x = pk2(x.x, x.y); w.y = pk2(x.z, x.w); *(u32x2*)(xp + bj * HALF + n * 16) = w; ss += (x.x * x.x + x.y * x.y) + (x.z * x.z + x.w * x.w); }
;                 ss += __shfl_xor(ss, 16); ss += __shfl_xor(ss, 32);
;                 if (fq == 0) sred[wc * 256 + ai * HALF + wr * 64 + m * 16 + fr] = ss; }
.LBB0_525:
	s_or_b64 exec, exec, s[52:53]
	v_or_b32_e32 v100, 32, v142
	v_ashrrev_i32_e32 v101, 31, v100
	v_lshlrev_b64 v[102:103], 13, v[100:101]
	s_waitcnt lgkmcnt(0)
	v_lshl_add_u64 v[96:97], s[12:13], 0, v[102:103]
	v_lshl_add_u64 v[104:105], v[96:97], 0, v[144:145]
	global_load_dwordx4 v[234:237], v[104:105], off
	global_load_dwordx4 v[238:241], v[104:105], off offset:64
	global_load_dwordx4 v[242:245], v[104:105], off offset:512
	global_load_dwordx4 v[246:249], v[104:105], off offset:576
	v_lshlrev_b64 v[100:101], 12, v[100:101]
	v_lshl_add_u64 v[102:103], s[20:21], 0, v[102:103]
	v_lshl_add_u64 v[100:101], s[22:23], 0, v[100:101]
	v_lshl_add_u64 v[102:103], v[102:103], 0, v[144:145]
	v_lshl_add_u64 v[100:101], v[140:141], 1, v[100:101]
	s_waitcnt vmcnt(3)
	v_pk_add_f32 v[94:95], v[94:95], v[236:237]
	v_pk_add_f32 v[92:93], v[92:93], v[234:235]
	v_cvt_pk_bf16_f32 v97, v94, v95
	v_cvt_pk_bf16_f32 v96, v92, v93
	global_store_dwordx4 v[102:103], v[92:95], off
	global_store_dwordx2 v[100:101], v[96:97], off
	s_nop 0
	v_mul_f32_e32 v93, v93, v93
	v_mul_f32_e32 v95, v95, v95
	v_fmac_f32_e32 v93, v92, v92
	v_fmac_f32_e32 v95, v94, v94
	v_add_f32_e32 v92, v93, v95
	s_waitcnt vmcnt(4)
	v_pk_add_f32 v[90:91], v[90:91], v[240:241]
	v_pk_add_f32 v[88:89], v[88:89], v[238:239]
	v_cvt_pk_bf16_f32 v97, v90, v91
	v_cvt_pk_bf16_f32 v96, v88, v89
	global_store_dwordx4 v[102:103], v[88:91], off offset:64
	global_store_dwordx2 v[100:101], v[96:97], off offset:32
	s_nop 0
	v_mul_f32_e32 v89, v89, v89
	v_mul_f32_e32 v91, v91, v91
	v_fmac_f32_e32 v89, v88, v88
	v_fmac_f32_e32 v91, v90, v90
	v_add_f32_e32 v88, v89, v91
	v_add_f32_e32 v88, v92, v88
	s_waitcnt vmcnt(5)
	v_pk_add_f32 v[86:87], v[86:87], v[244:245]
	v_pk_add_f32 v[84:85], v[84:85], v[242:243]
	v_cvt_pk_bf16_f32 v97, v86, v87
	v_cvt_pk_bf16_f32 v96, v84, v85
	global_store_dwordx4 v[102:103], v[84:87], off offset:512
	global_store_dwordx2 v[100:101], v[96:97], off offset:256
	s_nop 0
	v_mul_f32_e32 v85, v85, v85
	v_mul_f32_e32 v87, v87, v87
	v_fmac_f32_e32 v85, v84, v84
	v_fmac_f32_e32 v87, v86, v86
	v_add_f32_e32 v84, v85, v87
	v_add_f32_e32 v86, v88, v84
	s_waitcnt vmcnt(6)
	v_pk_add_f32 v[84:85], v[82:83], v[248:249]
	v_pk_add_f32 v[82:83], v[80:81], v[246:247]
	v_mul_f32_e32 v81, v85, v85
	v_mul_f32_e32 v80, v83, v83
	v_fmac_f32_e32 v80, v82, v82
	v_fmac_f32_e32 v81, v84, v84
	v_add_f32_e32 v80, v80, v81
	v_add_f32_e32 v80, v86, v80
	ds_bpermute_b32 v81, v116, v80
	global_store_dwordx4 v[102:103], v[82:85], off offset:576
	s_waitcnt lgkmcnt(0)
	v_add_f32_e32 v80, v80, v81
	ds_bpermute_b32 v81, v112, v80
	v_cvt_pk_bf16_f32 v82, v82, v83
	v_cvt_pk_bf16_f32 v83, v84, v85
	global_store_dwordx2 v[100:101], v[82:83], off offset:288
	s_and_saveexec_b64 s[52:53], s[4:5]
	s_cbranch_execz .LBB0_527
	s_waitcnt lgkmcnt(0)
	v_add_f32_e32 v80, v80, v81
	ds_write_b32 v149, v80 offset:128
.LBB0_527:
	s_or_b64 exec, exec, s[52:53]
	v_or_b32_e32 v84, 48, v142
	v_ashrrev_i32_e32 v85, 31, v84
	v_lshlrev_b64 v[86:87], 13, v[84:85]
	s_waitcnt lgkmcnt(0)
	v_lshl_add_u64 v[80:81], s[12:13], 0, v[86:87]
	v_lshl_add_u64 v[88:89], v[80:81], 0, v[144:145]
	global_load_dwordx4 v[234:237], v[88:89], off
	global_load_dwordx4 v[238:241], v[88:89], off offset:64
	global_load_dwordx4 v[242:245], v[88:89], off offset:512
	global_load_dwordx4 v[246:249], v[88:89], off offset:576
	v_lshlrev_b64 v[84:85], 12, v[84:85]
	v_lshl_add_u64 v[86:87], s[20:21], 0, v[86:87]
	v_lshl_add_u64 v[84:85], s[22:23], 0, v[84:85]
	v_lshl_add_u64 v[86:87], v[86:87], 0, v[144:145]
	v_lshl_add_u64 v[84:85], v[140:141], 1, v[84:85]
	s_waitcnt vmcnt(3)
	v_pk_add_f32 v[78:79], v[78:79], v[236:237]
	v_pk_add_f32 v[76:77], v[76:77], v[234:235]
	v_cvt_pk_bf16_f32 v81, v78, v79
	v_cvt_pk_bf16_f32 v80, v76, v77
	global_store_dwordx4 v[86:87], v[76:79], off
	global_store_dwordx2 v[84:85], v[80:81], off
	s_nop 0
	v_mul_f32_e32 v77, v77, v77
	v_mul_f32_e32 v79, v79, v79
	v_fmac_f32_e32 v77, v76, v76
	v_fmac_f32_e32 v79, v78, v78
	v_add_f32_e32 v76, v77, v79
	s_waitcnt vmcnt(4)
	v_pk_add_f32 v[74:75], v[74:75], v[240:241]
	v_pk_add_f32 v[72:73], v[72:73], v[238:239]
	v_cvt_pk_bf16_f32 v81, v74, v75
	v_cvt_pk_bf16_f32 v80, v72, v73
	global_store_dwordx4 v[86:87], v[72:75], off offset:64
	global_store_dwordx2 v[84:85], v[80:81], off offset:32
	s_nop 0
	v_mul_f32_e32 v73, v73, v73
	v_mul_f32_e32 v75, v75, v75
	v_fmac_f32_e32 v73, v72, v72
	v_fmac_f32_e32 v75, v74, v74
	v_add_f32_e32 v72, v73, v75
	v_add_f32_e32 v72, v76, v72
	s_waitcnt vmcnt(5)
	v_pk_add_f32 v[70:71], v[70:71], v[244:245]
	v_pk_add_f32 v[68:69], v[68:69], v[242:243]
	v_cvt_pk_bf16_f32 v81, v70, v71
	v_cvt_pk_bf16_f32 v80, v68, v69
	global_store_dwordx4 v[86:87], v[68:71], off offset:512
	global_store_dwordx2 v[84:85], v[80:81], off offset:256
	s_nop 0
	v_mul_f32_e32 v69, v69, v69
	v_mul_f32_e32 v71, v71, v71
	v_fmac_f32_e32 v69, v68, v68
	v_fmac_f32_e32 v71, v70, v70
	v_add_f32_e32 v68, v69, v71
	v_add_f32_e32 v70, v72, v68
	s_waitcnt vmcnt(6)
	v_pk_add_f32 v[68:69], v[66:67], v[248:249]
	v_pk_add_f32 v[66:67], v[64:65], v[246:247]
	v_mul_f32_e32 v65, v69, v69
	v_mul_f32_e32 v64, v67, v67
	v_fmac_f32_e32 v64, v66, v66
	v_fmac_f32_e32 v65, v68, v68
	v_add_f32_e32 v64, v64, v65
	v_add_f32_e32 v64, v70, v64
	ds_bpermute_b32 v65, v116, v64
	global_store_dwordx4 v[86:87], v[66:69], off offset:576
	s_waitcnt lgkmcnt(0)
	v_add_f32_e32 v64, v64, v65
	ds_bpermute_b32 v65, v112, v64
	v_cvt_pk_bf16_f32 v66, v66, v67
	v_cvt_pk_bf16_f32 v67, v68, v69
	global_store_dwordx2 v[84:85], v[66:67], off offset:288
	s_and_saveexec_b64 s[52:53], s[4:5]
	s_cbranch_execz .LBB0_529
	s_waitcnt lgkmcnt(0)
	v_add_f32_e32 v64, v64, v65
	ds_write_b32 v149, v64 offset:192
; __device__ __forceinline__ unsigned pk2(float lo, float hi) { f32x2_t v = {lo, hi}; bf16x2_t b = __builtin_convertvector(v, bf16x2_t); return __builtin_bit_cast(unsigned, b); }
;     __device__ __forceinline__ void operator()(const f32x4 (&acc)[2][2][4][2], const Unit& u, int wr, int wc, int fr, int fq) const {
;     ...
;             for (int m = 0; m < 4; ++m) { const int row = row0 + ai * HALF + m * 16;
;                 const float* bp = base + (size_t)row * D + col0; float* op = out + (size_t)row * D + col0; bf16_t* xp = xb + (size_t)row * D + col0;
;                 float ss = 0.f;
; #pragma unroll
;                 for (int bj = 0; bj < 2; ++bj)
; #pragma unroll
;                     for (int n = 0; n < 2; ++n) { const f32x4 b = *(const f32x4*)(bp + bj * HALF + n * 16); const f32x4 x = b + acc[ai][bj][m][n]; *(f32x4*)(op + bj * HALF + n * 16) = x;
;                         u32x2 w; w.x = pk2(x.x, x.y); w.y = pk2(x.z, x.w); *(u32x2*)(xp + bj * HALF + n * 16) = w; ss += (x.x * x.x + x.y * x.y) + (x.z * x.z + x.w * x.w); }
;                 ss += __shfl_xor(ss, 16); ss += __shfl_xor(ss, 32);
;                 if (fq == 0) sred[wc * 256 + ai * HALF + wr * 64 + m * 16 + fr] = ss; }
.LBB0_529:
	s_or_b64 exec, exec, s[52:53]
	v_add_u32_e32 v68, 0x80, v142
	v_ashrrev_i32_e32 v69, 31, v68
	v_lshlrev_b64 v[70:71], 13, v[68:69]
	s_waitcnt lgkmcnt(0)
	v_lshl_add_u64 v[64:65], s[12:13], 0, v[70:71]
	v_lshl_add_u64 v[72:73], v[64:65], 0, v[144:145]
	global_load_dwordx4 v[234:237], v[72:73], off
	global_load_dwordx4 v[238:241], v[72:73], off offset:64
	global_load_dwordx4 v[242:245], v[72:73], off offset:512
	global_load_dwordx4 v[246:249], v[72:73], off offset:576
	v_lshlrev_b64 v[68:69], 12, v[68:69]
	v_lshl_add_u64 v[70:71], s[20:21], 0, v[70:71]
	v_lshl_add_u64 v[68:69], s[22:23], 0, v[68:69]
	v_lshl_add_u64 v[70:71], v[70:71], 0, v[144:145]
	v_lshl_add_u64 v[68:69], v[140:141], 1, v[68:69]
	s_waitcnt vmcnt(3)
	v_pk_add_f32 v[62:63], v[62:63], v[236:237]
	v_pk_add_f32 v[60:61], v[60:61], v[234:235]
	v_cvt_pk_bf16_f32 v65, v62, v63
	v_cvt_pk_bf16_f32 v64, v60, v61
	global_store_dwordx4 v[70:71], v[60:63], off
	global_store_dwordx2 v[68:69], v[64:65], off
	s_nop 0
	v_mul_f32_e32 v61, v61, v61
	v_mul_f32_e32 v63, v63, v63
	v_fmac_f32_e32 v61, v60, v60
	v_fmac_f32_e32 v63, v62, v62
	v_add_f32_e32 v60, v61, v63
	s_waitcnt vmcnt(4)
	v_pk_add_f32 v[58:59], v[58:59], v[240:241]
	v_pk_add_f32 v[56:57], v[56:57], v[238:239]
	v_cvt_pk_bf16_f32 v65, v58, v59
	v_cvt_pk_bf16_f32 v64, v56, v57
	global_store_dwordx4 v[70:71], v[56:59], off offset:64
	global_store_dwordx2 v[68:69], v[64:65], off offset:32
	s_nop 0
	v_mul_f32_e32 v57, v57, v57
	v_mul_f32_e32 v59, v59, v59
	v_fmac_f32_e32 v57, v56, v56
	v_fmac_f32_e32 v59, v58, v58
	v_add_f32_e32 v56, v57, v59
	v_add_f32_e32 v56, v60, v56
	s_waitcnt vmcnt(5)
	v_pk_add_f32 v[54:55], v[54:55], v[244:245]
	v_pk_add_f32 v[52:53], v[52:53], v[242:243]
	v_cvt_pk_bf16_f32 v65, v54, v55
	v_cvt_pk_bf16_f32 v64, v52, v53
	global_store_dwordx4 v[70:71], v[52:55], off offset:512
	global_store_dwordx2 v[68:69], v[64:65], off offset:256
	s_nop 0
	v_mul_f32_e32 v53, v53, v53
	v_mul_f32_e32 v55, v55, v55
	v_fmac_f32_e32 v53, v52, v52
	v_fmac_f32_e32 v55, v54, v54
	v_add_f32_e32 v52, v53, v55
	v_add_f32_e32 v54, v56, v52
	s_waitcnt vmcnt(6)
	v_pk_add_f32 v[52:53], v[50:51], v[248:249]
	v_pk_add_f32 v[50:51], v[48:49], v[246:247]
	v_mul_f32_e32 v49, v53, v53
	v_mul_f32_e32 v48, v51, v51
	v_fmac_f32_e32 v48, v50, v50
	v_fmac_f32_e32 v49, v52, v52
	v_add_f32_e32 v48, v48, v49
	v_add_f32_e32 v48, v54, v48
	ds_bpermute_b32 v49, v116, v48
	global_store_dwordx4 v[70:71], v[50:53], off offset:576
	s_waitcnt lgkmcnt(0)
	v_add_f32_e32 v48, v48, v49
	ds_bpermute_b32 v49, v112, v48
	v_cvt_pk_bf16_f32 v50, v50, v51
	v_cvt_pk_bf16_f32 v51, v52, v53
	global_store_dwordx2 v[68:69], v[50:51], off offset:288
	s_and_saveexec_b64 s[52:53], s[4:5]
	s_cbranch_execz .LBB0_531
	s_waitcnt lgkmcnt(0)
	v_add_f32_e32 v48, v48, v49
	ds_write_b32 v149, v48 offset:512
.LBB0_531:
	s_or_b64 exec, exec, s[52:53]
	v_add_u32_e32 v52, 0x90, v142
	v_ashrrev_i32_e32 v53, 31, v52
	v_lshlrev_b64 v[54:55], 13, v[52:53]
	s_waitcnt lgkmcnt(0)
	v_lshl_add_u64 v[48:49], s[12:13], 0, v[54:55]
	v_lshl_add_u64 v[56:57], v[48:49], 0, v[144:145]
	global_load_dwordx4 v[234:237], v[56:57], off
	global_load_dwordx4 v[238:241], v[56:57], off offset:64
	global_load_dwordx4 v[242:245], v[56:57], off offset:512
	global_load_dwordx4 v[246:249], v[56:57], off offset:576
	v_lshlrev_b64 v[52:53], 12, v[52:53]
	v_lshl_add_u64 v[54:55], s[20:21], 0, v[54:55]
	v_lshl_add_u64 v[52:53], s[22:23], 0, v[52:53]
	v_lshl_add_u64 v[54:55], v[54:55], 0, v[144:145]
	v_lshl_add_u64 v[52:53], v[140:141], 1, v[52:53]
	s_waitcnt vmcnt(3)
	v_pk_add_f32 v[46:47], v[46:47], v[236:237]
	v_pk_add_f32 v[44:45], v[44:45], v[234:235]
	v_cvt_pk_bf16_f32 v49, v46, v47
	v_cvt_pk_bf16_f32 v48, v44, v45
	global_store_dwordx4 v[54:55], v[44:47], off
	global_store_dwordx2 v[52:53], v[48:49], off
	s_nop 0
	v_mul_f32_e32 v45, v45, v45
	v_mul_f32_e32 v47, v47, v47
	v_fmac_f32_e32 v45, v44, v44
	v_fmac_f32_e32 v47, v46, v46
	v_add_f32_e32 v44, v45, v47
	s_waitcnt vmcnt(4)
	v_pk_add_f32 v[42:43], v[42:43], v[240:241]
	v_pk_add_f32 v[40:41], v[40:41], v[238:239]
	v_cvt_pk_bf16_f32 v49, v42, v43
	v_cvt_pk_bf16_f32 v48, v40, v41
	global_store_dwordx4 v[54:55], v[40:43], off offset:64
	global_store_dwordx2 v[52:53], v[48:49], off offset:32
	s_nop 0
	v_mul_f32_e32 v41, v41, v41
	v_mul_f32_e32 v43, v43, v43
	v_fmac_f32_e32 v41, v40, v40
	v_fmac_f32_e32 v43, v42, v42
	v_add_f32_e32 v40, v41, v43
	v_add_f32_e32 v40, v44, v40
	s_waitcnt vmcnt(5)
	v_pk_add_f32 v[38:39], v[38:39], v[244:245]
	v_pk_add_f32 v[36:37], v[36:37], v[242:243]
	v_cvt_pk_bf16_f32 v49, v38, v39
	v_cvt_pk_bf16_f32 v48, v36, v37
	global_store_dwordx4 v[54:55], v[36:39], off offset:512
	global_store_dwordx2 v[52:53], v[48:49], off offset:256
	s_nop 0
	v_mul_f32_e32 v37, v37, v37
	v_mul_f32_e32 v39, v39, v39
	v_fmac_f32_e32 v37, v36, v36
	v_fmac_f32_e32 v39, v38, v38
	v_add_f32_e32 v36, v37, v39
	v_add_f32_e32 v38, v40, v36
	s_waitcnt vmcnt(6)
	v_pk_add_f32 v[36:37], v[34:35], v[248:249]
	v_pk_add_f32 v[34:35], v[32:33], v[246:247]
	v_mul_f32_e32 v33, v37, v37
	v_mul_f32_e32 v32, v35, v35
	v_fmac_f32_e32 v32, v34, v34
	v_fmac_f32_e32 v33, v36, v36
	v_add_f32_e32 v32, v32, v33
	v_add_f32_e32 v32, v38, v32
	ds_bpermute_b32 v33, v116, v32
	global_store_dwordx4 v[54:55], v[34:37], off offset:576
	s_waitcnt lgkmcnt(0)
	v_add_f32_e32 v32, v32, v33
	ds_bpermute_b32 v33, v112, v32
	v_cvt_pk_bf16_f32 v34, v34, v35
	v_cvt_pk_bf16_f32 v35, v36, v37
	global_store_dwordx2 v[52:53], v[34:35], off offset:288
	s_and_saveexec_b64 s[52:53], s[4:5]
	s_cbranch_execz .LBB0_533
	s_waitcnt lgkmcnt(0)
	v_add_f32_e32 v32, v32, v33
	ds_write_b32 v149, v32 offset:576
; __device__ __forceinline__ unsigned pk2(float lo, float hi) { f32x2_t v = {lo, hi}; bf16x2_t b = __builtin_convertvector(v, bf16x2_t); return __builtin_bit_cast(unsigned, b); }
;     __device__ __forceinline__ void operator()(const f32x4 (&acc)[2][2][4][2], const Unit& u, int wr, int wc, int fr, int fq) const {
;     ...
;             for (int m = 0; m < 4; ++m) { const int row = row0 + ai * HALF + m * 16;
;                 const float* bp = base + (size_t)row * D + col0; float* op = out + (size_t)row * D + col0; bf16_t* xp = xb + (size_t)row * D + col0;
;                 float ss = 0.f;
; #pragma unroll
;                 for (int bj = 0; bj < 2; ++bj)
; #pragma unroll
;                     for (int n = 0; n < 2; ++n) { const f32x4 b = *(const f32x4*)(bp + bj * HALF + n * 16); const f32x4 x = b + acc[ai][bj][m][n]; *(f32x4*)(op + bj * HALF + n * 16) = x;
;                         u32x2 w; w.x = pk2(x.x, x.y); w.y = pk2(x.z, x.w); *(u32x2*)(xp + bj * HALF + n * 16) = w; ss += (x.x * x.x + x.y * x.y) + (x.z * x.z + x.w * x.w); }
;                 ss += __shfl_xor(ss, 16); ss += __shfl_xor(ss, 32);
;                 if (fq == 0) sred[wc * 256 + ai * HALF + wr * 64 + m * 16 + fr] = ss; }
.LBB0_533:
	s_or_b64 exec, exec, s[52:53]
	v_add_u32_e32 v36, 0xa0, v142
	v_ashrrev_i32_e32 v37, 31, v36
	v_lshlrev_b64 v[38:39], 13, v[36:37]
	s_waitcnt lgkmcnt(0)
	v_lshl_add_u64 v[32:33], s[12:13], 0, v[38:39]
	v_lshl_add_u64 v[40:41], v[32:33], 0, v[144:145]
	global_load_dwordx4 v[234:237], v[40:41], off
	global_load_dwordx4 v[238:241], v[40:41], off offset:64
	global_load_dwordx4 v[242:245], v[40:41], off offset:512
	global_load_dwordx4 v[246:249], v[40:41], off offset:576
	v_lshlrev_b64 v[36:37], 12, v[36:37]
	v_lshl_add_u64 v[38:39], s[20:21], 0, v[38:39]
	v_lshl_add_u64 v[36:37], s[22:23], 0, v[36:37]
	v_lshl_add_u64 v[38:39], v[38:39], 0, v[144:145]
	v_lshl_add_u64 v[36:37], v[140:141], 1, v[36:37]
	s_waitcnt vmcnt(3)
	v_pk_add_f32 v[30:31], v[30:31], v[236:237]
	v_pk_add_f32 v[28:29], v[28:29], v[234:235]
	v_cvt_pk_bf16_f32 v33, v30, v31
	v_cvt_pk_bf16_f32 v32, v28, v29
	global_store_dwordx4 v[38:39], v[28:31], off
	global_store_dwordx2 v[36:37], v[32:33], off
	s_nop 0
	v_mul_f32_e32 v29, v29, v29
	v_mul_f32_e32 v31, v31, v31
	v_fmac_f32_e32 v29, v28, v28
	v_fmac_f32_e32 v31, v30, v30
	v_add_f32_e32 v28, v29, v31
	s_waitcnt vmcnt(4)
	v_pk_add_f32 v[26:27], v[26:27], v[240:241]
	v_pk_add_f32 v[24:25], v[24:25], v[238:239]
	v_cvt_pk_bf16_f32 v33, v26, v27
	v_cvt_pk_bf16_f32 v32, v24, v25
	global_store_dwordx4 v[38:39], v[24:27], off offset:64
	global_store_dwordx2 v[36:37], v[32:33], off offset:32
	s_nop 0
	v_mul_f32_e32 v25, v25, v25
	v_mul_f32_e32 v27, v27, v27
	v_fmac_f32_e32 v25, v24, v24
	v_fmac_f32_e32 v27, v26, v26
	v_add_f32_e32 v24, v25, v27
	v_add_f32_e32 v24, v28, v24
	s_waitcnt vmcnt(5)
	v_pk_add_f32 v[22:23], v[22:23], v[244:245]
	v_pk_add_f32 v[20:21], v[20:21], v[242:243]
	v_cvt_pk_bf16_f32 v33, v22, v23
	v_cvt_pk_bf16_f32 v32, v20, v21
	global_store_dwordx4 v[38:39], v[20:23], off offset:512
	global_store_dwordx2 v[36:37], v[32:33], off offset:256
	s_nop 0
	v_mul_f32_e32 v21, v21, v21
	v_mul_f32_e32 v23, v23, v23
	v_fmac_f32_e32 v21, v20, v20
	v_fmac_f32_e32 v23, v22, v22
	v_add_f32_e32 v20, v21, v23
	v_add_f32_e32 v22, v24, v20
	s_waitcnt vmcnt(6)
	v_pk_add_f32 v[20:21], v[18:19], v[248:249]
	v_pk_add_f32 v[18:19], v[16:17], v[246:247]
	v_mul_f32_e32 v17, v21, v21
	v_mul_f32_e32 v16, v19, v19
	v_fmac_f32_e32 v16, v18, v18
	v_fmac_f32_e32 v17, v20, v20
	v_add_f32_e32 v16, v16, v17
	v_add_f32_e32 v16, v22, v16
	ds_bpermute_b32 v17, v116, v16
	global_store_dwordx4 v[38:39], v[18:21], off offset:576
	s_waitcnt lgkmcnt(0)
	v_add_f32_e32 v16, v16, v17
	ds_bpermute_b32 v17, v112, v16
	v_cvt_pk_bf16_f32 v18, v18, v19
	v_cvt_pk_bf16_f32 v19, v20, v21
	global_store_dwordx2 v[36:37], v[18:19], off offset:288
	s_and_saveexec_b64 s[52:53], s[4:5]
	s_cbranch_execz .LBB0_535
	s_waitcnt lgkmcnt(0)
	v_add_f32_e32 v16, v16, v17
	ds_write_b32 v149, v16 offset:640
.LBB0_535:
	s_or_b64 exec, exec, s[52:53]
	v_add_u32_e32 v20, 0xb0, v142
	v_ashrrev_i32_e32 v21, 31, v20
	v_lshlrev_b64 v[22:23], 13, v[20:21]
	s_waitcnt lgkmcnt(0)
	v_lshl_add_u64 v[16:17], s[12:13], 0, v[22:23]
	v_lshl_add_u64 v[24:25], v[16:17], 0, v[144:145]
	global_load_dwordx4 v[234:237], v[24:25], off
	global_load_dwordx4 v[238:241], v[24:25], off offset:64
	global_load_dwordx4 v[242:245], v[24:25], off offset:512
	global_load_dwordx4 v[246:249], v[24:25], off offset:576
	v_lshlrev_b64 v[20:21], 12, v[20:21]
	v_lshl_add_u64 v[22:23], s[20:21], 0, v[22:23]
	v_lshl_add_u64 v[20:21], s[22:23], 0, v[20:21]
	v_lshl_add_u64 v[22:23], v[22:23], 0, v[144:145]
	v_lshl_add_u64 v[20:21], v[140:141], 1, v[20:21]
	s_waitcnt vmcnt(3)
	v_pk_add_f32 v[14:15], v[14:15], v[236:237]
	v_pk_add_f32 v[12:13], v[12:13], v[234:235]
	v_cvt_pk_bf16_f32 v17, v14, v15
	v_cvt_pk_bf16_f32 v16, v12, v13
	global_store_dwordx4 v[22:23], v[12:15], off
	global_store_dwordx2 v[20:21], v[16:17], off
	s_nop 0
	v_mul_f32_e32 v13, v13, v13
	v_mul_f32_e32 v15, v15, v15
	v_fmac_f32_e32 v13, v12, v12
	v_fmac_f32_e32 v15, v14, v14
	v_add_f32_e32 v12, v13, v15
	s_waitcnt vmcnt(4)
	v_pk_add_f32 v[10:11], v[10:11], v[240:241]
	v_pk_add_f32 v[8:9], v[8:9], v[238:239]
	v_cvt_pk_bf16_f32 v17, v10, v11
	v_cvt_pk_bf16_f32 v16, v8, v9
	global_store_dwordx4 v[22:23], v[8:11], off offset:64
	global_store_dwordx2 v[20:21], v[16:17], off offset:32
	s_nop 0
	v_mul_f32_e32 v9, v9, v9
	v_mul_f32_e32 v11, v11, v11
	v_fmac_f32_e32 v9, v8, v8
	v_fmac_f32_e32 v11, v10, v10
	v_add_f32_e32 v8, v9, v11
	v_add_f32_e32 v8, v12, v8
	s_waitcnt vmcnt(5)
	v_pk_add_f32 v[6:7], v[6:7], v[244:245]
	v_pk_add_f32 v[4:5], v[4:5], v[242:243]
	v_cvt_pk_bf16_f32 v17, v6, v7
	v_cvt_pk_bf16_f32 v16, v4, v5
	global_store_dwordx4 v[22:23], v[4:7], off offset:512
	global_store_dwordx2 v[20:21], v[16:17], off offset:256
	s_nop 0
	v_mul_f32_e32 v5, v5, v5
	v_mul_f32_e32 v7, v7, v7
	v_fmac_f32_e32 v5, v4, v4
	v_fmac_f32_e32 v7, v6, v6
	v_add_f32_e32 v4, v5, v7
	v_add_f32_e32 v6, v8, v4
	s_waitcnt vmcnt(6)
	v_pk_add_f32 v[4:5], v[2:3], v[248:249]
	v_pk_add_f32 v[2:3], v[0:1], v[246:247]
	v_mul_f32_e32 v1, v5, v5
	v_mul_f32_e32 v0, v3, v3
	v_fmac_f32_e32 v0, v2, v2
	v_fmac_f32_e32 v1, v4, v4
	v_add_f32_e32 v0, v0, v1
	v_add_f32_e32 v0, v6, v0
	ds_bpermute_b32 v1, v116, v0
	global_store_dwordx4 v[22:23], v[2:5], off offset:576
	s_waitcnt lgkmcnt(0)
	v_add_f32_e32 v0, v0, v1
	ds_bpermute_b32 v1, v112, v0
	v_cvt_pk_bf16_f32 v2, v2, v3
	v_cvt_pk_bf16_f32 v3, v4, v5
	global_store_dwordx2 v[20:21], v[2:3], off offset:288
	s_and_saveexec_b64 s[52:53], s[4:5]
	s_cbranch_execz .LBB0_537
	s_waitcnt lgkmcnt(0)
	v_add_f32_e32 v0, v0, v1
	ds_write_b32 v149, v0 offset:704

; __device__ __forceinline__ unsigned pk2(float lo, float hi) { f32x2_t v = {lo, hi}; bf16x2_t b = __builtin_convertvector(v, bf16x2_t); return __builtin_bit_cast(unsigned, b); }
;     __device__ __forceinline__ void operator()(const f32x4 (&acc)[2][2][4][2], const Unit& u, int wr, int wc, int fr, int fq) const {
;     ...
;             for (int m = 0; m < 4; ++m) { const int row = row0 + ai * HALF + m * 16;
;                 const float* bp = base + (size_t)row * D + col0; float* op = out + (size_t)row * D + col0; bf16_t* xp = xb + (size_t)row * D + col0;
;                 float ss = 0.f;
; #pragma unroll
;                 for (int bj = 0; bj < 2; ++bj)
; #pragma unroll
;                     for (int n = 0; n < 2; ++n) { const f32x4 b = *(const f32x4*)(bp + bj * HALF + n * 16); const f32x4 x = b + acc[ai][bj][m][n]; *(f32x4*)(op + bj * HALF + n * 16) = x;
;                         u32x2 w; w.x = pk2(x.x, x.y); w.y = pk2(x.z, x.w); *(u32x2*)(xp + bj * HALF + n * 16) = w; ss += (x.x * x.x + x.y * x.y) + (x.z * x.z + x.w * x.w); }
;                 ss += __shfl_xor(ss, 16); ss += __shfl_xor(ss, 32);
;                 if (fq == 0) sred[wc * 256 + ai * HALF + wr * 64 + m * 16 + fr] = ss; }
.LBB0_728:
	s_lshl_b32 s11, s50, 8
	v_add_u32_e32 v142, s11, v144
	v_ashrrev_i32_e32 v143, 31, v142
	v_lshl_or_b32 v140, s10, 8, v146
	v_lshlrev_b64 v[154:155], 13, v[142:143]
	v_ashrrev_i32_e32 v141, 31, v140
	v_lshl_add_u64 v[154:155], s[14:15], 0, v[154:155]
	v_lshl_add_u64 v[162:163], v[140:141], 2, v[154:155]
	global_load_dwordx4 v[234:237], v[162:163], off
	global_load_dwordx4 v[238:241], v[162:163], off offset:64
	global_load_dwordx4 v[242:245], v[162:163], off offset:512
	global_load_dwordx4 v[246:249], v[162:163], off offset:576
	v_lshlrev_b64 v[158:159], 12, v[142:143]
	v_lshl_add_u64 v[158:159], s[18:19], 0, v[158:159]
	v_lshl_add_u64 v[164:165], v[140:141], 1, v[158:159]
	s_waitcnt vmcnt(3)
	v_pk_add_f32 v[126:127], v[126:127], v[236:237]
	v_pk_add_f32 v[124:125], v[124:125], v[234:235]
	v_cvt_pk_bf16_f32 v155, v126, v127
	v_cvt_pk_bf16_f32 v154, v124, v125
	global_store_dwordx4 v[162:163], v[124:127], off
	global_store_dwordx2 v[164:165], v[154:155], off
	s_waitcnt vmcnt(4)
	v_pk_add_f32 v[122:123], v[122:123], v[240:241]
	v_pk_add_f32 v[120:121], v[120:121], v[238:239]
	v_cvt_pk_bf16_f32 v155, v122, v123
	v_cvt_pk_bf16_f32 v154, v120, v121
	global_store_dwordx4 v[162:163], v[120:123], off offset:64
	global_store_dwordx2 v[164:165], v[154:155], off offset:32
	s_waitcnt vmcnt(5)
	v_pk_add_f32 v[156:157], v[118:119], v[244:245]
	v_pk_add_f32 v[154:155], v[116:117], v[242:243]
	v_cvt_pk_bf16_f32 v117, v156, v157
	v_cvt_pk_bf16_f32 v116, v154, v155
	global_store_dwordx4 v[162:163], v[154:157], off offset:512
	global_store_dwordx2 v[164:165], v[116:117], off offset:256
	v_mul_f32_e32 v118, v125, v125
	v_mul_f32_e32 v119, v127, v127
	v_fmac_f32_e32 v118, v124, v124
	v_fmac_f32_e32 v119, v126, v126
	v_add_f32_e32 v118, v118, v119
	v_mul_f32_e32 v119, v121, v121
	v_mul_f32_e32 v121, v123, v123
	v_fmac_f32_e32 v119, v120, v120
	v_fmac_f32_e32 v121, v122, v122
	v_add_f32_e32 v119, v119, v121
	v_add_f32_e32 v118, v118, v119
	v_mul_f32_e32 v119, v155, v155
	v_mul_f32_e32 v120, v157, v157
	v_fmac_f32_e32 v119, v154, v154
	v_fmac_f32_e32 v120, v156, v156
	v_add_f32_e32 v119, v119, v120
	v_and_b32_e32 v117, 64, v152
	v_add_f32_e32 v122, v118, v119
	v_xor_b32_e32 v116, 16, v152
	v_add_u32_e32 v117, 64, v117
	v_cmp_lt_i32_e32 vcc, v116, v117
	s_waitcnt vmcnt(6)
	v_pk_add_f32 v[120:121], v[114:115], v[248:249]
	v_pk_add_f32 v[118:119], v[112:113], v[246:247]
	v_mul_f32_e32 v113, v121, v121
	v_mul_f32_e32 v112, v119, v119
	v_fmac_f32_e32 v112, v118, v118
	v_fmac_f32_e32 v113, v120, v120
	v_cndmask_b32_e32 v116, v152, v116, vcc
	v_add_f32_e32 v112, v112, v113
	v_lshlrev_b32_e32 v116, 2, v116
	v_add_f32_e32 v113, v122, v112
	ds_bpermute_b32 v114, v116, v113
	v_xor_b32_e32 v112, 32, v152
	v_cmp_lt_i32_e32 vcc, v112, v117
	global_store_dwordx4 v[162:163], v[118:121], off offset:576
	s_waitcnt lgkmcnt(0)
	v_add_f32_e32 v113, v113, v114
	v_cndmask_b32_e32 v112, v152, v112, vcc
	v_lshlrev_b32_e32 v112, 2, v112
	ds_bpermute_b32 v114, v112, v113
	v_cvt_pk_bf16_f32 v118, v118, v119
	v_cvt_pk_bf16_f32 v119, v120, v121
	global_store_dwordx2 v[164:165], v[118:119], off offset:288
	s_and_saveexec_b64 s[50:51], s[4:5]
	s_cbranch_execz .LBB0_730
	s_waitcnt lgkmcnt(0)
	v_add_f32_e32 v113, v113, v114
	ds_write_b32 v147, v113
.LBB0_730:
	s_or_b64 exec, exec, s[50:51]
	s_waitcnt lgkmcnt(0)
	v_or_b32_e32 v114, 16, v142
	v_ashrrev_i32_e32 v115, 31, v114
	v_lshlrev_b64 v[118:119], 13, v[114:115]
	v_lshl_add_u64 v[118:119], s[14:15], 0, v[118:119]
	v_lshl_add_u64 v[122:123], v[140:141], 2, v[118:119]
	global_load_dwordx4 v[234:237], v[122:123], off
	global_load_dwordx4 v[238:241], v[122:123], off offset:64
	global_load_dwordx4 v[242:245], v[122:123], off offset:512
	global_load_dwordx4 v[246:249], v[122:123], off offset:576
	v_lshlrev_b64 v[114:115], 12, v[114:115]
	v_lshl_add_u64 v[114:115], s[18:19], 0, v[114:115]
	v_lshl_add_u64 v[114:115], v[140:141], 1, v[114:115]
	s_waitcnt vmcnt(3)
	v_pk_add_f32 v[110:111], v[110:111], v[236:237]
	v_pk_add_f32 v[108:109], v[108:109], v[234:235]
	v_cvt_pk_bf16_f32 v119, v110, v111
	v_cvt_pk_bf16_f32 v118, v108, v109
	global_store_dwordx4 v[122:123], v[108:111], off
	global_store_dwordx2 v[114:115], v[118:119], off
	s_nop 0
	v_mul_f32_e32 v109, v109, v109
	v_mul_f32_e32 v111, v111, v111
	v_fmac_f32_e32 v109, v108, v108
	v_fmac_f32_e32 v111, v110, v110
	v_add_f32_e32 v108, v109, v111
	s_waitcnt vmcnt(4)
	v_pk_add_f32 v[106:107], v[106:107], v[240:241]
	v_pk_add_f32 v[104:105], v[104:105], v[238:239]
	v_cvt_pk_bf16_f32 v119, v106, v107
	v_cvt_pk_bf16_f32 v118, v104, v105
	global_store_dwordx4 v[122:123], v[104:107], off offset:64
	global_store_dwordx2 v[114:115], v[118:119], off offset:32
	s_nop 0
	v_mul_f32_e32 v105, v105, v105
	v_mul_f32_e32 v107, v107, v107
	v_fmac_f32_e32 v105, v104, v104
	v_fmac_f32_e32 v107, v106, v106
	v_add_f32_e32 v104, v105, v107
	v_add_f32_e32 v104, v108, v104
	s_waitcnt vmcnt(5)
	v_pk_add_f32 v[102:103], v[102:103], v[244:245]
	v_pk_add_f32 v[100:101], v[100:101], v[242:243]
	v_cvt_pk_bf16_f32 v119, v102, v103
	v_cvt_pk_bf16_f32 v118, v100, v101
	global_store_dwordx4 v[122:123], v[100:103], off offset:512
	global_store_dwordx2 v[114:115], v[118:119], off offset:256
	s_nop 0
	v_mul_f32_e32 v101, v101, v101
	v_mul_f32_e32 v103, v103, v103
	v_fmac_f32_e32 v101, v100, v100
	v_fmac_f32_e32 v103, v102, v102
	v_add_f32_e32 v100, v101, v103
	v_add_f32_e32 v102, v104, v100
	s_waitcnt vmcnt(6)
	v_pk_add_f32 v[100:101], v[98:99], v[248:249]
	v_pk_add_f32 v[98:99], v[96:97], v[246:247]
	v_mul_f32_e32 v97, v101, v101
	v_mul_f32_e32 v96, v99, v99
	v_fmac_f32_e32 v96, v98, v98
	v_fmac_f32_e32 v97, v100, v100
	v_add_f32_e32 v96, v96, v97
	v_add_f32_e32 v96, v102, v96
	ds_bpermute_b32 v97, v116, v96
	global_store_dwordx4 v[122:123], v[98:101], off offset:576
	s_waitcnt lgkmcnt(0)
	v_add_f32_e32 v96, v96, v97
	ds_bpermute_b32 v97, v112, v96
	v_cvt_pk_bf16_f32 v98, v98, v99
	v_cvt_pk_bf16_f32 v99, v100, v101
	global_store_dwordx2 v[114:115], v[98:99], off offset:288
	s_and_saveexec_b64 s[50:51], s[4:5]
	s_cbranch_execz .LBB0_732
	s_waitcnt lgkmcnt(0)
	v_add_f32_e32 v96, v96, v97
	ds_write_b32 v147, v96 offset:64
; __device__ __forceinline__ unsigned pk2(float lo, float hi) { f32x2_t v = {lo, hi}; bf16x2_t b = __builtin_convertvector(v, bf16x2_t); return __builtin_bit_cast(unsigned, b); }
;     __device__ __forceinline__ void operator()(const f32x4 (&acc)[2][2][4][2], const Unit& u, int wr, int wc, int fr, int fq) const {
;     ...
;             for (int m = 0; m < 4; ++m) { const int row = row0 + ai * HALF + m * 16;
;                 const float* bp = base + (size_t)row * D + col0; float* op = out + (size_t)row * D + col0; bf16_t* xp = xb + (size_t)row * D + col0;
;                 float ss = 0.f;
; #pragma unroll
;                 for (int bj = 0; bj < 2; ++bj)
; #pragma unroll
;                     for (int n = 0; n < 2; ++n) { const f32x4 b = *(const f32x4*)(bp + bj * HALF + n * 16); const f32x4 x = b + acc[ai][bj][m][n]; *(f32x4*)(op + bj * HALF + n * 16) = x;
;                         u32x2 w; w.x = pk2(x.x, x.y); w.y = pk2(x.z, x.w); *(u32x2*)(xp + bj * HALF + n * 16) = w; ss += (x.x * x.x + x.y * x.y) + (x.z * x.z + x.w * x.w); }
;                 ss += __shfl_xor(ss, 16); ss += __shfl_xor(ss, 32);
;                 if (fq == 0) sred[wc * 256 + ai * HALF + wr * 64 + m * 16 + fr] = ss; }
.LBB0_732:
	s_or_b64 exec, exec, s[50:51]
	v_or_b32_e32 v100, 32, v142
	v_ashrrev_i32_e32 v101, 31, v100
	s_waitcnt lgkmcnt(0)
	v_lshlrev_b64 v[96:97], 13, v[100:101]
	v_lshl_add_u64 v[96:97], s[14:15], 0, v[96:97]
	v_lshl_add_u64 v[102:103], v[140:141], 2, v[96:97]
	global_load_dwordx4 v[234:237], v[102:103], off
	global_load_dwordx4 v[238:241], v[102:103], off offset:64
	global_load_dwordx4 v[242:245], v[102:103], off offset:512
	global_load_dwordx4 v[246:249], v[102:103], off offset:576
	v_lshlrev_b64 v[100:101], 12, v[100:101]
	v_lshl_add_u64 v[100:101], s[18:19], 0, v[100:101]
	v_lshl_add_u64 v[100:101], v[140:141], 1, v[100:101]
	s_waitcnt vmcnt(3)
	v_pk_add_f32 v[94:95], v[94:95], v[236:237]
	v_pk_add_f32 v[92:93], v[92:93], v[234:235]
	v_cvt_pk_bf16_f32 v97, v94, v95
	v_cvt_pk_bf16_f32 v96, v92, v93
	global_store_dwordx4 v[102:103], v[92:95], off
	global_store_dwordx2 v[100:101], v[96:97], off
	s_nop 0
	v_mul_f32_e32 v93, v93, v93
	v_mul_f32_e32 v95, v95, v95
	v_fmac_f32_e32 v93, v92, v92
	v_fmac_f32_e32 v95, v94, v94
	v_add_f32_e32 v92, v93, v95
	s_waitcnt vmcnt(4)
	v_pk_add_f32 v[90:91], v[90:91], v[240:241]
	v_pk_add_f32 v[88:89], v[88:89], v[238:239]
	v_cvt_pk_bf16_f32 v97, v90, v91
	v_cvt_pk_bf16_f32 v96, v88, v89
	global_store_dwordx4 v[102:103], v[88:91], off offset:64
	global_store_dwordx2 v[100:101], v[96:97], off offset:32
	s_nop 0
	v_mul_f32_e32 v89, v89, v89
	v_mul_f32_e32 v91, v91, v91
	v_fmac_f32_e32 v89, v88, v88
	v_fmac_f32_e32 v91, v90, v90
	v_add_f32_e32 v88, v89, v91
	v_add_f32_e32 v88, v92, v88
	s_waitcnt vmcnt(5)
	v_pk_add_f32 v[86:87], v[86:87], v[244:245]
	v_pk_add_f32 v[84:85], v[84:85], v[242:243]
	v_cvt_pk_bf16_f32 v97, v86, v87
	v_cvt_pk_bf16_f32 v96, v84, v85
	global_store_dwordx4 v[102:103], v[84:87], off offset:512
	global_store_dwordx2 v[100:101], v[96:97], off offset:256
	s_nop 0
	v_mul_f32_e32 v85, v85, v85
	v_mul_f32_e32 v87, v87, v87
	v_fmac_f32_e32 v85, v84, v84
	v_fmac_f32_e32 v87, v86, v86
	v_add_f32_e32 v84, v85, v87
	v_add_f32_e32 v86, v88, v84
	s_waitcnt vmcnt(6)
	v_pk_add_f32 v[84:85], v[82:83], v[248:249]
	v_pk_add_f32 v[82:83], v[80:81], v[246:247]
	v_mul_f32_e32 v81, v85, v85
	v_mul_f32_e32 v80, v83, v83
	v_fmac_f32_e32 v80, v82, v82
	v_fmac_f32_e32 v81, v84, v84
	v_add_f32_e32 v80, v80, v81
	v_add_f32_e32 v80, v86, v80
	ds_bpermute_b32 v81, v116, v80
	global_store_dwordx4 v[102:103], v[82:85], off offset:576
	s_waitcnt lgkmcnt(0)
	v_add_f32_e32 v80, v80, v81
	ds_bpermute_b32 v81, v112, v80
	v_cvt_pk_bf16_f32 v82, v82, v83
	v_cvt_pk_bf16_f32 v83, v84, v85
	global_store_dwordx2 v[100:101], v[82:83], off offset:288
	s_and_saveexec_b64 s[50:51], s[4:5]
	s_cbranch_execz .LBB0_734
	s_waitcnt lgkmcnt(0)
	v_add_f32_e32 v80, v80, v81
	ds_write_b32 v147, v80 offset:128
.LBB0_734:
	s_or_b64 exec, exec, s[50:51]
	v_or_b32_e32 v84, 48, v142
	v_ashrrev_i32_e32 v85, 31, v84
	s_waitcnt lgkmcnt(0)
	v_lshlrev_b64 v[80:81], 13, v[84:85]
	v_lshl_add_u64 v[80:81], s[14:15], 0, v[80:81]
	v_lshl_add_u64 v[86:87], v[140:141], 2, v[80:81]
	global_load_dwordx4 v[234:237], v[86:87], off
	global_load_dwordx4 v[238:241], v[86:87], off offset:64
	global_load_dwordx4 v[242:245], v[86:87], off offset:512
	global_load_dwordx4 v[246:249], v[86:87], off offset:576
	v_lshlrev_b64 v[84:85], 12, v[84:85]
	v_lshl_add_u64 v[84:85], s[18:19], 0, v[84:85]
	v_lshl_add_u64 v[84:85], v[140:141], 1, v[84:85]
	s_waitcnt vmcnt(3)
	v_pk_add_f32 v[78:79], v[78:79], v[236:237]
	v_pk_add_f32 v[76:77], v[76:77], v[234:235]
	v_cvt_pk_bf16_f32 v81, v78, v79
	v_cvt_pk_bf16_f32 v80, v76, v77
	global_store_dwordx4 v[86:87], v[76:79], off
	global_store_dwordx2 v[84:85], v[80:81], off
	s_nop 0
	v_mul_f32_e32 v77, v77, v77
	v_mul_f32_e32 v79, v79, v79
	v_fmac_f32_e32 v77, v76, v76
	v_fmac_f32_e32 v79, v78, v78
	v_add_f32_e32 v76, v77, v79
	s_waitcnt vmcnt(4)
	v_pk_add_f32 v[74:75], v[74:75], v[240:241]
	v_pk_add_f32 v[72:73], v[72:73], v[238:239]
	v_cvt_pk_bf16_f32 v81, v74, v75
	v_cvt_pk_bf16_f32 v80, v72, v73
	global_store_dwordx4 v[86:87], v[72:75], off offset:64
	global_store_dwordx2 v[84:85], v[80:81], off offset:32
	s_nop 0
	v_mul_f32_e32 v73, v73, v73
	v_mul_f32_e32 v75, v75, v75
	v_fmac_f32_e32 v73, v72, v72
	v_fmac_f32_e32 v75, v74, v74
	v_add_f32_e32 v72, v73, v75
	v_add_f32_e32 v72, v76, v72
	s_waitcnt vmcnt(5)
	v_pk_add_f32 v[70:71], v[70:71], v[244:245]
	v_pk_add_f32 v[68:69], v[68:69], v[242:243]
	v_cvt_pk_bf16_f32 v81, v70, v71
	v_cvt_pk_bf16_f32 v80, v68, v69
	global_store_dwordx4 v[86:87], v[68:71], off offset:512
	global_store_dwordx2 v[84:85], v[80:81], off offset:256
	s_nop 0
	v_mul_f32_e32 v69, v69, v69
	v_mul_f32_e32 v71, v71, v71
	v_fmac_f32_e32 v69, v68, v68
	v_fmac_f32_e32 v71, v70, v70
	v_add_f32_e32 v68, v69, v71
	v_add_f32_e32 v70, v72, v68
	s_waitcnt vmcnt(6)
	v_pk_add_f32 v[68:69], v[66:67], v[248:249]
	v_pk_add_f32 v[66:67], v[64:65], v[246:247]
	v_mul_f32_e32 v65, v69, v69
	v_mul_f32_e32 v64, v67, v67
	v_fmac_f32_e32 v64, v66, v66
	v_fmac_f32_e32 v65, v68, v68
	v_add_f32_e32 v64, v64, v65
	v_add_f32_e32 v64, v70, v64
	ds_bpermute_b32 v65, v116, v64
	global_store_dwordx4 v[86:87], v[66:69], off offset:576
	s_waitcnt lgkmcnt(0)
	v_add_f32_e32 v64, v64, v65
	ds_bpermute_b32 v65, v112, v64
	v_cvt_pk_bf16_f32 v66, v66, v67
	v_cvt_pk_bf16_f32 v67, v68, v69
	global_store_dwordx2 v[84:85], v[66:67], off offset:288
	s_and_saveexec_b64 s[50:51], s[4:5]
	s_cbranch_execz .LBB0_736
	s_waitcnt lgkmcnt(0)
	v_add_f32_e32 v64, v64, v65
	ds_write_b32 v147, v64 offset:192
; __device__ __forceinline__ unsigned pk2(float lo, float hi) { f32x2_t v = {lo, hi}; bf16x2_t b = __builtin_convertvector(v, bf16x2_t); return __builtin_bit_cast(unsigned, b); }
;     __device__ __forceinline__ void operator()(const f32x4 (&acc)[2][2][4][2], const Unit& u, int wr, int wc, int fr, int fq) const {
;     ...
;             for (int m = 0; m < 4; ++m) { const int row = row0 + ai * HALF + m * 16;
;                 const float* bp = base + (size_t)row * D + col0; float* op = out + (size_t)row * D + col0; bf16_t* xp = xb + (size_t)row * D + col0;
;                 float ss = 0.f;
; #pragma unroll
;                 for (int bj = 0; bj < 2; ++bj)
; #pragma unroll
;                     for (int n = 0; n < 2; ++n) { const f32x4 b = *(const f32x4*)(bp + bj * HALF + n * 16); const f32x4 x = b + acc[ai][bj][m][n]; *(f32x4*)(op + bj * HALF + n * 16) = x;
;                         u32x2 w; w.x = pk2(x.x, x.y); w.y = pk2(x.z, x.w); *(u32x2*)(xp + bj * HALF + n * 16) = w; ss += (x.x * x.x + x.y * x.y) + (x.z * x.z + x.w * x.w); }
;                 ss += __shfl_xor(ss, 16); ss += __shfl_xor(ss, 32);
;                 if (fq == 0) sred[wc * 256 + ai * HALF + wr * 64 + m * 16 + fr] = ss; }
.LBB0_736:
	s_or_b64 exec, exec, s[50:51]
	v_add_u32_e32 v68, 0x80, v142
	v_ashrrev_i32_e32 v69, 31, v68
	s_waitcnt lgkmcnt(0)
	v_lshlrev_b64 v[64:65], 13, v[68:69]
	v_lshl_add_u64 v[64:65], s[14:15], 0, v[64:65]
	v_lshl_add_u64 v[70:71], v[140:141], 2, v[64:65]
	global_load_dwordx4 v[234:237], v[70:71], off
	global_load_dwordx4 v[238:241], v[70:71], off offset:64
	global_load_dwordx4 v[242:245], v[70:71], off offset:512
	global_load_dwordx4 v[246:249], v[70:71], off offset:576
	v_lshlrev_b64 v[68:69], 12, v[68:69]
	v_lshl_add_u64 v[68:69], s[18:19], 0, v[68:69]
	v_lshl_add_u64 v[68:69], v[140:141], 1, v[68:69]
	s_waitcnt vmcnt(3)
	v_pk_add_f32 v[62:63], v[62:63], v[236:237]
	v_pk_add_f32 v[60:61], v[60:61], v[234:235]
	v_cvt_pk_bf16_f32 v65, v62, v63
	v_cvt_pk_bf16_f32 v64, v60, v61
	global_store_dwordx4 v[70:71], v[60:63], off
	global_store_dwordx2 v[68:69], v[64:65], off
	s_nop 0
	v_mul_f32_e32 v61, v61, v61
	v_mul_f32_e32 v63, v63, v63
	v_fmac_f32_e32 v61, v60, v60
	v_fmac_f32_e32 v63, v62, v62
	v_add_f32_e32 v60, v61, v63
	s_waitcnt vmcnt(4)
	v_pk_add_f32 v[58:59], v[58:59], v[240:241]
	v_pk_add_f32 v[56:57], v[56:57], v[238:239]
	v_cvt_pk_bf16_f32 v65, v58, v59
	v_cvt_pk_bf16_f32 v64, v56, v57
	global_store_dwordx4 v[70:71], v[56:59], off offset:64
	global_store_dwordx2 v[68:69], v[64:65], off offset:32
	s_nop 0
	v_mul_f32_e32 v57, v57, v57
	v_mul_f32_e32 v59, v59, v59
	v_fmac_f32_e32 v57, v56, v56
	v_fmac_f32_e32 v59, v58, v58
	v_add_f32_e32 v56, v57, v59
	v_add_f32_e32 v56, v60, v56
	s_waitcnt vmcnt(5)
	v_pk_add_f32 v[54:55], v[54:55], v[244:245]
	v_pk_add_f32 v[52:53], v[52:53], v[242:243]
	v_cvt_pk_bf16_f32 v65, v54, v55
	v_cvt_pk_bf16_f32 v64, v52, v53
	global_store_dwordx4 v[70:71], v[52:55], off offset:512
	global_store_dwordx2 v[68:69], v[64:65], off offset:256
	s_nop 0
	v_mul_f32_e32 v53, v53, v53
	v_mul_f32_e32 v55, v55, v55
	v_fmac_f32_e32 v53, v52, v52
	v_fmac_f32_e32 v55, v54, v54
	v_add_f32_e32 v52, v53, v55
	v_add_f32_e32 v54, v56, v52
	s_waitcnt vmcnt(6)
	v_pk_add_f32 v[52:53], v[50:51], v[248:249]
	v_pk_add_f32 v[50:51], v[48:49], v[246:247]
	v_mul_f32_e32 v49, v53, v53
	v_mul_f32_e32 v48, v51, v51
	v_fmac_f32_e32 v48, v50, v50
	v_fmac_f32_e32 v49, v52, v52
	v_add_f32_e32 v48, v48, v49
	v_add_f32_e32 v48, v54, v48
	ds_bpermute_b32 v49, v116, v48
	global_store_dwordx4 v[70:71], v[50:53], off offset:576
	s_waitcnt lgkmcnt(0)
	v_add_f32_e32 v48, v48, v49
	ds_bpermute_b32 v49, v112, v48
	v_cvt_pk_bf16_f32 v50, v50, v51
	v_cvt_pk_bf16_f32 v51, v52, v53
	global_store_dwordx2 v[68:69], v[50:51], off offset:288
	s_and_saveexec_b64 s[50:51], s[4:5]
	s_cbranch_execz .LBB0_738
	s_waitcnt lgkmcnt(0)
	v_add_f32_e32 v48, v48, v49
	ds_write_b32 v147, v48 offset:512
.LBB0_738:
	s_or_b64 exec, exec, s[50:51]
	v_add_u32_e32 v52, 0x90, v142
	v_ashrrev_i32_e32 v53, 31, v52
	s_waitcnt lgkmcnt(0)
	v_lshlrev_b64 v[48:49], 13, v[52:53]
	v_lshl_add_u64 v[48:49], s[14:15], 0, v[48:49]
	v_lshl_add_u64 v[54:55], v[140:141], 2, v[48:49]
	global_load_dwordx4 v[234:237], v[54:55], off
	global_load_dwordx4 v[238:241], v[54:55], off offset:64
	global_load_dwordx4 v[242:245], v[54:55], off offset:512
	global_load_dwordx4 v[246:249], v[54:55], off offset:576
	v_lshlrev_b64 v[52:53], 12, v[52:53]
	v_lshl_add_u64 v[52:53], s[18:19], 0, v[52:53]
	v_lshl_add_u64 v[52:53], v[140:141], 1, v[52:53]
	s_waitcnt vmcnt(3)
	v_pk_add_f32 v[46:47], v[46:47], v[236:237]
	v_pk_add_f32 v[44:45], v[44:45], v[234:235]
	v_cvt_pk_bf16_f32 v49, v46, v47
	v_cvt_pk_bf16_f32 v48, v44, v45
	global_store_dwordx4 v[54:55], v[44:47], off
	global_store_dwordx2 v[52:53], v[48:49], off
	s_nop 0
	v_mul_f32_e32 v45, v45, v45
	v_mul_f32_e32 v47, v47, v47
	v_fmac_f32_e32 v45, v44, v44
	v_fmac_f32_e32 v47, v46, v46
	v_add_f32_e32 v44, v45, v47
	s_waitcnt vmcnt(4)
	v_pk_add_f32 v[42:43], v[42:43], v[240:241]
	v_pk_add_f32 v[40:41], v[40:41], v[238:239]
	v_cvt_pk_bf16_f32 v49, v42, v43
	v_cvt_pk_bf16_f32 v48, v40, v41
	global_store_dwordx4 v[54:55], v[40:43], off offset:64
	global_store_dwordx2 v[52:53], v[48:49], off offset:32
	s_nop 0
	v_mul_f32_e32 v41, v41, v41
	v_mul_f32_e32 v43, v43, v43
	v_fmac_f32_e32 v41, v40, v40
	v_fmac_f32_e32 v43, v42, v42
	v_add_f32_e32 v40, v41, v43
	v_add_f32_e32 v40, v44, v40
	s_waitcnt vmcnt(5)
	v_pk_add_f32 v[38:39], v[38:39], v[244:245]
	v_pk_add_f32 v[36:37], v[36:37], v[242:243]
	v_cvt_pk_bf16_f32 v49, v38, v39
	v_cvt_pk_bf16_f32 v48, v36, v37
	global_store_dwordx4 v[54:55], v[36:39], off offset:512
	global_store_dwordx2 v[52:53], v[48:49], off offset:256
	s_nop 0
	v_mul_f32_e32 v37, v37, v37
	v_mul_f32_e32 v39, v39, v39
	v_fmac_f32_e32 v37, v36, v36
	v_fmac_f32_e32 v39, v38, v38
	v_add_f32_e32 v36, v37, v39
	v_add_f32_e32 v38, v40, v36
	s_waitcnt vmcnt(6)
	v_pk_add_f32 v[36:37], v[34:35], v[248:249]
	v_pk_add_f32 v[34:35], v[32:33], v[246:247]
	v_mul_f32_e32 v33, v37, v37
	v_mul_f32_e32 v32, v35, v35
	v_fmac_f32_e32 v32, v34, v34
	v_fmac_f32_e32 v33, v36, v36
	v_add_f32_e32 v32, v32, v33
	v_add_f32_e32 v32, v38, v32
	ds_bpermute_b32 v33, v116, v32
	global_store_dwordx4 v[54:55], v[34:37], off offset:576
	s_waitcnt lgkmcnt(0)
	v_add_f32_e32 v32, v32, v33
	ds_bpermute_b32 v33, v112, v32
	v_cvt_pk_bf16_f32 v34, v34, v35
	v_cvt_pk_bf16_f32 v35, v36, v37
	global_store_dwordx2 v[52:53], v[34:35], off offset:288
	s_and_saveexec_b64 s[50:51], s[4:5]
	s_cbranch_execz .LBB0_740
	s_waitcnt lgkmcnt(0)
	v_add_f32_e32 v32, v32, v33
	ds_write_b32 v147, v32 offset:576
; __device__ __forceinline__ unsigned pk2(float lo, float hi) { f32x2_t v = {lo, hi}; bf16x2_t b = __builtin_convertvector(v, bf16x2_t); return __builtin_bit_cast(unsigned, b); }
;     __device__ __forceinline__ void operator()(const f32x4 (&acc)[2][2][4][2], const Unit& u, int wr, int wc, int fr, int fq) const {
;     ...
;             for (int m = 0; m < 4; ++m) { const int row = row0 + ai * HALF + m * 16;
;                 const float* bp = base + (size_t)row * D + col0; float* op = out + (size_t)row * D + col0; bf16_t* xp = xb + (size_t)row * D + col0;
;                 float ss = 0.f;
; #pragma unroll
;                 for (int bj = 0; bj < 2; ++bj)
; #pragma unroll
;                     for (int n = 0; n < 2; ++n) { const f32x4 b = *(const f32x4*)(bp + bj * HALF + n * 16); const f32x4 x = b + acc[ai][bj][m][n]; *(f32x4*)(op + bj * HALF + n * 16) = x;
;                         u32x2 w; w.x = pk2(x.x, x.y); w.y = pk2(x.z, x.w); *(u32x2*)(xp + bj * HALF + n * 16) = w; ss += (x.x * x.x + x.y * x.y) + (x.z * x.z + x.w * x.w); }
;                 ss += __shfl_xor(ss, 16); ss += __shfl_xor(ss, 32);
;                 if (fq == 0) sred[wc * 256 + ai * HALF + wr * 64 + m * 16 + fr] = ss; }
.LBB0_740:
	s_or_b64 exec, exec, s[50:51]
	v_add_u32_e32 v36, 0xa0, v142
	v_ashrrev_i32_e32 v37, 31, v36
	s_waitcnt lgkmcnt(0)
	v_lshlrev_b64 v[32:33], 13, v[36:37]
	v_lshl_add_u64 v[32:33], s[14:15], 0, v[32:33]
	v_lshl_add_u64 v[38:39], v[140:141], 2, v[32:33]
	global_load_dwordx4 v[234:237], v[38:39], off
	global_load_dwordx4 v[238:241], v[38:39], off offset:64
	global_load_dwordx4 v[242:245], v[38:39], off offset:512
	global_load_dwordx4 v[246:249], v[38:39], off offset:576
	v_lshlrev_b64 v[36:37], 12, v[36:37]
	v_lshl_add_u64 v[36:37], s[18:19], 0, v[36:37]
	v_lshl_add_u64 v[36:37], v[140:141], 1, v[36:37]
	s_waitcnt vmcnt(3)
	v_pk_add_f32 v[30:31], v[30:31], v[236:237]
	v_pk_add_f32 v[28:29], v[28:29], v[234:235]
	v_cvt_pk_bf16_f32 v33, v30, v31
	v_cvt_pk_bf16_f32 v32, v28, v29
	global_store_dwordx4 v[38:39], v[28:31], off
	global_store_dwordx2 v[36:37], v[32:33], off
	s_nop 0
	v_mul_f32_e32 v29, v29, v29
	v_mul_f32_e32 v31, v31, v31
	v_fmac_f32_e32 v29, v28, v28
	v_fmac_f32_e32 v31, v30, v30
	v_add_f32_e32 v28, v29, v31
	s_waitcnt vmcnt(4)
	v_pk_add_f32 v[26:27], v[26:27], v[240:241]
	v_pk_add_f32 v[24:25], v[24:25], v[238:239]
	v_cvt_pk_bf16_f32 v33, v26, v27
	v_cvt_pk_bf16_f32 v32, v24, v25
	global_store_dwordx4 v[38:39], v[24:27], off offset:64
	global_store_dwordx2 v[36:37], v[32:33], off offset:32
	s_nop 0
	v_mul_f32_e32 v25, v25, v25
	v_mul_f32_e32 v27, v27, v27
	v_fmac_f32_e32 v25, v24, v24
	v_fmac_f32_e32 v27, v26, v26
	v_add_f32_e32 v24, v25, v27
	v_add_f32_e32 v24, v28, v24
	s_waitcnt vmcnt(5)
	v_pk_add_f32 v[22:23], v[22:23], v[244:245]
	v_pk_add_f32 v[20:21], v[20:21], v[242:243]
	v_cvt_pk_bf16_f32 v33, v22, v23
	v_cvt_pk_bf16_f32 v32, v20, v21
	global_store_dwordx4 v[38:39], v[20:23], off offset:512
	global_store_dwordx2 v[36:37], v[32:33], off offset:256
	s_nop 0
	v_mul_f32_e32 v21, v21, v21
	v_mul_f32_e32 v23, v23, v23
	v_fmac_f32_e32 v21, v20, v20
	v_fmac_f32_e32 v23, v22, v22
	v_add_f32_e32 v20, v21, v23
	v_add_f32_e32 v22, v24, v20
	s_waitcnt vmcnt(6)
	v_pk_add_f32 v[20:21], v[18:19], v[248:249]
	v_pk_add_f32 v[18:19], v[16:17], v[246:247]
	v_mul_f32_e32 v17, v21, v21
	v_mul_f32_e32 v16, v19, v19
	v_fmac_f32_e32 v16, v18, v18
	v_fmac_f32_e32 v17, v20, v20
	v_add_f32_e32 v16, v16, v17
	v_add_f32_e32 v16, v22, v16
	ds_bpermute_b32 v17, v116, v16
	global_store_dwordx4 v[38:39], v[18:21], off offset:576
	s_waitcnt lgkmcnt(0)
	v_add_f32_e32 v16, v16, v17
	ds_bpermute_b32 v17, v112, v16
	v_cvt_pk_bf16_f32 v18, v18, v19
	v_cvt_pk_bf16_f32 v19, v20, v21
	global_store_dwordx2 v[36:37], v[18:19], off offset:288
	s_and_saveexec_b64 s[50:51], s[4:5]
	s_cbranch_execz .LBB0_742
	s_waitcnt lgkmcnt(0)
	v_add_f32_e32 v16, v16, v17
	ds_write_b32 v147, v16 offset:640
.LBB0_742:
	s_or_b64 exec, exec, s[50:51]
	v_add_u32_e32 v20, 0xb0, v142
	v_ashrrev_i32_e32 v21, 31, v20
	s_waitcnt lgkmcnt(0)
	v_lshlrev_b64 v[16:17], 13, v[20:21]
	v_lshl_add_u64 v[16:17], s[14:15], 0, v[16:17]
	v_lshl_add_u64 v[22:23], v[140:141], 2, v[16:17]
	global_load_dwordx4 v[234:237], v[22:23], off
	global_load_dwordx4 v[238:241], v[22:23], off offset:64
	global_load_dwordx4 v[242:245], v[22:23], off offset:512
	global_load_dwordx4 v[246:249], v[22:23], off offset:576
	v_lshlrev_b64 v[20:21], 12, v[20:21]
	v_lshl_add_u64 v[20:21], s[18:19], 0, v[20:21]
	v_lshl_add_u64 v[20:21], v[140:141], 1, v[20:21]
	s_waitcnt vmcnt(3)
	v_pk_add_f32 v[14:15], v[14:15], v[236:237]
	v_pk_add_f32 v[12:13], v[12:13], v[234:235]
	v_cvt_pk_bf16_f32 v17, v14, v15
	v_cvt_pk_bf16_f32 v16, v12, v13
	global_store_dwordx4 v[22:23], v[12:15], off
	global_store_dwordx2 v[20:21], v[16:17], off
	s_nop 0
	v_mul_f32_e32 v13, v13, v13
	v_mul_f32_e32 v15, v15, v15
	v_fmac_f32_e32 v13, v12, v12
	v_fmac_f32_e32 v15, v14, v14
	v_add_f32_e32 v12, v13, v15
	s_waitcnt vmcnt(4)
	v_pk_add_f32 v[10:11], v[10:11], v[240:241]
	v_pk_add_f32 v[8:9], v[8:9], v[238:239]
	v_cvt_pk_bf16_f32 v17, v10, v11
	v_cvt_pk_bf16_f32 v16, v8, v9
	global_store_dwordx4 v[22:23], v[8:11], off offset:64
	global_store_dwordx2 v[20:21], v[16:17], off offset:32
	s_nop 0
	v_mul_f32_e32 v9, v9, v9
	v_mul_f32_e32 v11, v11, v11
	v_fmac_f32_e32 v9, v8, v8
	v_fmac_f32_e32 v11, v10, v10
	v_add_f32_e32 v8, v9, v11
	v_add_f32_e32 v8, v12, v8
	s_waitcnt vmcnt(5)
	v_pk_add_f32 v[6:7], v[6:7], v[244:245]
	v_pk_add_f32 v[4:5], v[4:5], v[242:243]
	v_cvt_pk_bf16_f32 v17, v6, v7
	v_cvt_pk_bf16_f32 v16, v4, v5
	global_store_dwordx4 v[22:23], v[4:7], off offset:512
	global_store_dwordx2 v[20:21], v[16:17], off offset:256
	s_nop 0
	v_mul_f32_e32 v5, v5, v5
	v_mul_f32_e32 v7, v7, v7
	v_fmac_f32_e32 v5, v4, v4
	v_fmac_f32_e32 v7, v6, v6
	v_add_f32_e32 v4, v5, v7
	v_add_f32_e32 v6, v8, v4
	s_waitcnt vmcnt(6)
	v_pk_add_f32 v[4:5], v[2:3], v[248:249]
	v_pk_add_f32 v[2:3], v[0:1], v[246:247]
	v_mul_f32_e32 v1, v5, v5
	v_mul_f32_e32 v0, v3, v3
	v_fmac_f32_e32 v0, v2, v2
	v_fmac_f32_e32 v1, v4, v4
	v_add_f32_e32 v0, v0, v1
	v_add_f32_e32 v0, v6, v0
	ds_bpermute_b32 v1, v116, v0
	global_store_dwordx4 v[22:23], v[2:5], off offset:576
	s_waitcnt lgkmcnt(0)
	v_add_f32_e32 v0, v0, v1
	ds_bpermute_b32 v1, v112, v0
	v_cvt_pk_bf16_f32 v2, v2, v3
	v_cvt_pk_bf16_f32 v3, v4, v5
	global_store_dwordx2 v[20:21], v[2:3], off offset:288
	s_and_saveexec_b64 s[50:51], s[4:5]
	s_cbranch_execz .LBB0_744
	s_waitcnt lgkmcnt(0)
	v_add_f32_e32 v0, v0, v1
	ds_write_b32 v147, v0 offset:704

;     __device__ __forceinline__ void operator()(const f32x4 (&acc)[2][2][4][2], const Unit& u, int wr, int wc, int fr, int fq) const {
;     ...
;         for (int ai = 0; ai < 2; ++ai)
; #pragma unroll
;             for (int m = 0; m < 4; ++m) { const int row = row0 + ai * HALF + m * 16;
;                 if (row < nrows) {
;                     const float* bp = (row < split ? base0 + (size_t)row * D : base1 + (size_t)(row - split) * D) + col0; float* op = out + (size_t)row * D + col0;
; #pragma unroll
;                     for (int bj = 0; bj < 2; ++bj)
; #pragma unroll
;                         for (int n = 0; n < 2; ++n) { const f32x4 b = *(const f32x4*)(bp + bj * HALF + n * 16); *(f32x4*)(op + bj * HALF + n * 16) = b + acc[ai][bj][m][n]; } } }
.LBB0_901:
	v_lshl_or_b32 v140, s57, 8, v146
	v_lshl_add_u32 v142, s56, 8, v144
	v_ashrrev_i32_e32 v141, 31, v140
	v_cmp_gt_i32_e32 vcc, s43, v142
	v_ashrrev_i32_e32 v143, 31, v142
	v_lshlrev_b64 v[140:141], 2, v[140:141]
	s_and_saveexec_b64 s[26:27], vcc
	s_cbranch_execz .LBB0_903
	v_lshlrev_b64 v[154:155], 13, v[142:143]
	v_lshl_add_u64 v[150:151], s[10:11], 0, v[154:155]
	v_lshl_add_u64 v[156:157], v[150:151], 0, v[140:141]
	global_load_dwordx4 v[234:237], v[156:157], off
	global_load_dwordx4 v[238:241], v[156:157], off offset:64
	global_load_dwordx4 v[242:245], v[156:157], off offset:512
	global_load_dwordx4 v[246:249], v[156:157], off offset:576
	v_lshl_add_u64 v[154:155], s[8:9], 0, v[154:155]
	v_lshl_add_u64 v[154:155], v[154:155], 0, v[140:141]
	s_waitcnt vmcnt(3)
	v_pk_add_f32 v[126:127], v[126:127], v[236:237]
	v_pk_add_f32 v[124:125], v[124:125], v[234:235]
	global_store_dwordx4 v[154:155], v[124:127], off
	s_waitcnt vmcnt(3)
	v_pk_add_f32 v[122:123], v[122:123], v[240:241]
	v_pk_add_f32 v[120:121], v[120:121], v[238:239]
	global_store_dwordx4 v[154:155], v[120:123], off offset:64
	s_waitcnt vmcnt(3)
	v_pk_add_f32 v[118:119], v[118:119], v[244:245]
	v_pk_add_f32 v[116:117], v[116:117], v[242:243]
	global_store_dwordx4 v[154:155], v[116:119], off offset:512
	s_waitcnt vmcnt(3)
	v_pk_add_f32 v[114:115], v[114:115], v[248:249]
	v_pk_add_f32 v[112:113], v[112:113], v[246:247]
	global_store_dwordx4 v[154:155], v[112:115], off offset:576
.LBB0_903:
	s_or_b64 exec, exec, s[26:27]
	s_nop 0
	v_or_b32_e32 v112, 16, v142
	v_cmp_gt_i32_e32 vcc, s43, v112
	s_and_saveexec_b64 s[26:27], vcc
	s_cbranch_execz .LBB0_905
	v_ashrrev_i32_e32 v113, 31, v112
	v_lshlrev_b64 v[116:117], 13, v[112:113]
	v_lshl_add_u64 v[112:113], s[10:11], 0, v[116:117]
	v_lshl_add_u64 v[118:119], v[112:113], 0, v[140:141]
	global_load_dwordx4 v[234:237], v[118:119], off
	global_load_dwordx4 v[238:241], v[118:119], off offset:64
	global_load_dwordx4 v[242:245], v[118:119], off offset:512
	global_load_dwordx4 v[246:249], v[118:119], off offset:576
	v_lshl_add_u64 v[116:117], s[8:9], 0, v[116:117]
	v_lshl_add_u64 v[116:117], v[116:117], 0, v[140:141]
	s_waitcnt vmcnt(3)
	v_pk_add_f32 v[110:111], v[110:111], v[236:237]
	v_pk_add_f32 v[108:109], v[108:109], v[234:235]
	global_store_dwordx4 v[116:117], v[108:111], off
	s_waitcnt vmcnt(3)
	v_pk_add_f32 v[106:107], v[106:107], v[240:241]
	v_pk_add_f32 v[104:105], v[104:105], v[238:239]
	global_store_dwordx4 v[116:117], v[104:107], off offset:64
	s_waitcnt vmcnt(3)
	v_pk_add_f32 v[102:103], v[102:103], v[244:245]
	v_pk_add_f32 v[100:101], v[100:101], v[242:243]
	global_store_dwordx4 v[116:117], v[100:103], off offset:512
	s_waitcnt vmcnt(3)
	v_pk_add_f32 v[98:99], v[98:99], v[248:249]
	v_pk_add_f32 v[96:97], v[96:97], v[246:247]
	global_store_dwordx4 v[116:117], v[96:99], off offset:576
.LBB0_905:
	s_or_b64 exec, exec, s[26:27]
	s_nop 0
	v_or_b32_e32 v96, 32, v142
	v_cmp_gt_i32_e32 vcc, s43, v96
	s_and_saveexec_b64 s[26:27], vcc
	s_cbranch_execz .LBB0_907
	v_ashrrev_i32_e32 v97, 31, v96
	v_lshlrev_b64 v[100:101], 13, v[96:97]
	v_lshl_add_u64 v[96:97], s[10:11], 0, v[100:101]
	v_lshl_add_u64 v[102:103], v[96:97], 0, v[140:141]
	global_load_dwordx4 v[234:237], v[102:103], off
	global_load_dwordx4 v[238:241], v[102:103], off offset:64
	global_load_dwordx4 v[242:245], v[102:103], off offset:512
	global_load_dwordx4 v[246:249], v[102:103], off offset:576
	v_lshl_add_u64 v[100:101], s[8:9], 0, v[100:101]
	v_lshl_add_u64 v[100:101], v[100:101], 0, v[140:141]
	s_waitcnt vmcnt(3)
	v_pk_add_f32 v[94:95], v[94:95], v[236:237]
	v_pk_add_f32 v[92:93], v[92:93], v[234:235]
	global_store_dwordx4 v[100:101], v[92:95], off
	s_waitcnt vmcnt(3)
	v_pk_add_f32 v[90:91], v[90:91], v[240:241]
	v_pk_add_f32 v[88:89], v[88:89], v[238:239]
	global_store_dwordx4 v[100:101], v[88:91], off offset:64
	s_waitcnt vmcnt(3)
	v_pk_add_f32 v[86:87], v[86:87], v[244:245]
	v_pk_add_f32 v[84:85], v[84:85], v[242:243]
	global_store_dwordx4 v[100:101], v[84:87], off offset:512
	s_waitcnt vmcnt(3)
	v_pk_add_f32 v[82:83], v[82:83], v[248:249]
	v_pk_add_f32 v[80:81], v[80:81], v[246:247]
	global_store_dwordx4 v[100:101], v[80:83], off offset:576

;     __device__ __forceinline__ void operator()(const f32x4 (&acc)[2][2][4][2], const Unit& u, int wr, int wc, int fr, int fq) const {
;     ...
;         for (int ai = 0; ai < 2; ++ai)
; #pragma unroll
;             for (int m = 0; m < 4; ++m) { const int row = row0 + ai * HALF + m * 16;
;                 if (row < nrows) {
;                     const float* bp = (row < split ? base0 + (size_t)row * D : base1 + (size_t)(row - split) * D) + col0; float* op = out + (size_t)row * D + col0;
; #pragma unroll
;                     for (int bj = 0; bj < 2; ++bj)
; #pragma unroll
;                         for (int n = 0; n < 2; ++n) { const f32x4 b = *(const f32x4*)(bp + bj * HALF + n * 16); *(f32x4*)(op + bj * HALF + n * 16) = b + acc[ai][bj][m][n]; } } }
.LBB0_913:
	v_ashrrev_i32_e32 v81, 31, v80
	v_lshlrev_b64 v[84:85], 13, v[80:81]
	v_lshl_add_u64 v[80:81], s[10:11], 0, v[84:85]
	v_lshl_add_u64 v[86:87], v[80:81], 0, v[140:141]
	global_load_dwordx4 v[234:237], v[86:87], off
	global_load_dwordx4 v[238:241], v[86:87], off offset:64
	global_load_dwordx4 v[242:245], v[86:87], off offset:512
	global_load_dwordx4 v[246:249], v[86:87], off offset:576
	v_lshl_add_u64 v[84:85], s[8:9], 0, v[84:85]
	v_lshl_add_u64 v[84:85], v[84:85], 0, v[140:141]
	s_waitcnt vmcnt(3)
	v_pk_add_f32 v[78:79], v[78:79], v[236:237]
	v_pk_add_f32 v[76:77], v[76:77], v[234:235]
	global_store_dwordx4 v[84:85], v[76:79], off
	s_waitcnt vmcnt(3)
	v_pk_add_f32 v[74:75], v[74:75], v[240:241]
	v_pk_add_f32 v[72:73], v[72:73], v[238:239]
	global_store_dwordx4 v[84:85], v[72:75], off offset:64
	s_waitcnt vmcnt(3)
	v_pk_add_f32 v[70:71], v[70:71], v[244:245]
	v_pk_add_f32 v[68:69], v[68:69], v[242:243]
	global_store_dwordx4 v[84:85], v[68:71], off offset:512
	s_waitcnt vmcnt(3)
	v_pk_add_f32 v[66:67], v[66:67], v[248:249]
	v_pk_add_f32 v[64:65], v[64:65], v[246:247]
	global_store_dwordx4 v[84:85], v[64:67], off offset:576
	s_or_b64 exec, exec, s[26:27]
	v_cmp_gt_i32_e32 vcc, s50, v142
	s_and_saveexec_b64 s[26:27], vcc
	s_cbranch_execz .LBB0_909
.LBB0_914:
	v_lshlrev_b64 v[64:65], 13, v[142:143]
	v_lshl_add_u64 v[68:69], v[64:65], 0, s[18:19]
	v_lshl_add_u64 v[64:65], s[10:11], 0, v[68:69]
	v_lshl_add_u64 v[70:71], v[64:65], 0, v[140:141]
	global_load_dwordx4 v[234:237], v[70:71], off
	global_load_dwordx4 v[238:241], v[70:71], off offset:64
	global_load_dwordx4 v[242:245], v[70:71], off offset:512
	global_load_dwordx4 v[246:249], v[70:71], off offset:576
	v_lshl_add_u64 v[68:69], s[8:9], 0, v[68:69]
	v_lshl_add_u64 v[68:69], v[68:69], 0, v[140:141]
	s_waitcnt vmcnt(3)
	v_pk_add_f32 v[62:63], v[62:63], v[236:237]
	v_pk_add_f32 v[60:61], v[60:61], v[234:235]
	global_store_dwordx4 v[68:69], v[60:63], off
	s_waitcnt vmcnt(3)
	v_pk_add_f32 v[58:59], v[58:59], v[240:241]
	v_pk_add_f32 v[56:57], v[56:57], v[238:239]
	global_store_dwordx4 v[68:69], v[56:59], off offset:64
	s_waitcnt vmcnt(3)
	v_pk_add_f32 v[54:55], v[54:55], v[244:245]
	v_pk_add_f32 v[52:53], v[52:53], v[242:243]
	global_store_dwordx4 v[68:69], v[52:55], off offset:512
	s_waitcnt vmcnt(3)
	v_pk_add_f32 v[50:51], v[50:51], v[248:249]
	v_pk_add_f32 v[48:49], v[48:49], v[246:247]
	global_store_dwordx4 v[68:69], v[48:51], off offset:576
	s_or_b64 exec, exec, s[26:27]
	v_cmp_gt_i32_e32 vcc, s51, v142
	s_and_saveexec_b64 s[26:27], vcc
	s_cbranch_execz .LBB0_910
.LBB0_915:
	v_lshlrev_b64 v[48:49], 13, v[142:143]
	v_lshl_add_u64 v[52:53], v[48:49], 0, s[20:21]
	v_lshl_add_u64 v[48:49], s[10:11], 0, v[52:53]
	v_lshl_add_u64 v[54:55], v[48:49], 0, v[140:141]
	global_load_dwordx4 v[234:237], v[54:55], off
	global_load_dwordx4 v[238:241], v[54:55], off offset:64
	global_load_dwordx4 v[242:245], v[54:55], off offset:512
	global_load_dwordx4 v[246:249], v[54:55], off offset:576
	v_lshl_add_u64 v[52:53], s[8:9], 0, v[52:53]
	v_lshl_add_u64 v[52:53], v[52:53], 0, v[140:141]
	s_waitcnt vmcnt(3)
	v_pk_add_f32 v[46:47], v[46:47], v[236:237]
	v_pk_add_f32 v[44:45], v[44:45], v[234:235]
	global_store_dwordx4 v[52:53], v[44:47], off
	s_waitcnt vmcnt(3)
	v_pk_add_f32 v[42:43], v[42:43], v[240:241]
	v_pk_add_f32 v[40:41], v[40:41], v[238:239]
	global_store_dwordx4 v[52:53], v[40:43], off offset:64
	s_waitcnt vmcnt(3)
	v_pk_add_f32 v[38:39], v[38:39], v[244:245]
	v_pk_add_f32 v[36:37], v[36:37], v[242:243]
	global_store_dwordx4 v[52:53], v[36:39], off offset:512
	s_waitcnt vmcnt(3)
	v_pk_add_f32 v[34:35], v[34:35], v[248:249]
	v_pk_add_f32 v[32:33], v[32:33], v[246:247]
	global_store_dwordx4 v[52:53], v[32:35], off offset:576
	s_or_b64 exec, exec, s[26:27]
	v_cmp_gt_i32_e32 vcc, s52, v142
	s_and_saveexec_b64 s[26:27], vcc
	s_cbranch_execz .LBB0_911
.LBB0_916:
	v_lshlrev_b64 v[32:33], 13, v[142:143]
	v_lshl_add_u64 v[36:37], v[32:33], 0, s[22:23]
	v_lshl_add_u64 v[32:33], s[10:11], 0, v[36:37]
	v_lshl_add_u64 v[38:39], v[32:33], 0, v[140:141]
	global_load_dwordx4 v[234:237], v[38:39], off
	global_load_dwordx4 v[238:241], v[38:39], off offset:64
	global_load_dwordx4 v[242:245], v[38:39], off offset:512
	global_load_dwordx4 v[246:249], v[38:39], off offset:576
	v_lshl_add_u64 v[36:37], s[8:9], 0, v[36:37]
	v_lshl_add_u64 v[36:37], v[36:37], 0, v[140:141]
	s_waitcnt vmcnt(3)
	v_pk_add_f32 v[30:31], v[30:31], v[236:237]
	v_pk_add_f32 v[28:29], v[28:29], v[234:235]
	global_store_dwordx4 v[36:37], v[28:31], off
	s_waitcnt vmcnt(3)
	v_pk_add_f32 v[26:27], v[26:27], v[240:241]
	v_pk_add_f32 v[24:25], v[24:25], v[238:239]
	global_store_dwordx4 v[36:37], v[24:27], off offset:64
	s_waitcnt vmcnt(3)
	v_pk_add_f32 v[22:23], v[22:23], v[244:245]
	v_pk_add_f32 v[20:21], v[20:21], v[242:243]
	global_store_dwordx4 v[36:37], v[20:23], off offset:512
	s_waitcnt vmcnt(3)
	v_pk_add_f32 v[18:19], v[18:19], v[248:249]
	v_pk_add_f32 v[16:17], v[16:17], v[246:247]
	global_store_dwordx4 v[36:37], v[16:19], off offset:576
	s_or_b64 exec, exec, s[26:27]
	v_cmp_gt_i32_e32 vcc, s53, v142
	s_and_saveexec_b64 s[26:27], vcc
	s_cbranch_execz .LBB0_912
.LBB0_917:
	v_lshlrev_b64 v[16:17], 13, v[142:143]
	v_lshl_add_u64 v[20:21], v[16:17], 0, s[6:7]
	v_lshl_add_u64 v[16:17], s[10:11], 0, v[20:21]
	v_lshl_add_u64 v[22:23], v[16:17], 0, v[140:141]
	global_load_dwordx4 v[234:237], v[22:23], off
	global_load_dwordx4 v[238:241], v[22:23], off offset:64
	global_load_dwordx4 v[242:245], v[22:23], off offset:512
	global_load_dwordx4 v[246:249], v[22:23], off offset:576
	v_lshl_add_u64 v[20:21], s[8:9], 0, v[20:21]
	v_lshl_add_u64 v[20:21], v[20:21], 0, v[140:141]
	s_waitcnt vmcnt(3)
	v_pk_add_f32 v[14:15], v[14:15], v[236:237]
	v_pk_add_f32 v[12:13], v[12:13], v[234:235]
	global_store_dwordx4 v[20:21], v[12:15], off
	s_waitcnt vmcnt(3)
	v_pk_add_f32 v[10:11], v[10:11], v[240:241]
	v_pk_add_f32 v[8:9], v[8:9], v[238:239]
	global_store_dwordx4 v[20:21], v[8:11], off offset:64
	s_waitcnt vmcnt(3)
	v_pk_add_f32 v[6:7], v[6:7], v[244:245]
	v_pk_add_f32 v[4:5], v[4:5], v[242:243]
	global_store_dwordx4 v[20:21], v[4:7], off offset:512
	s_waitcnt vmcnt(3)
	v_pk_add_f32 v[2:3], v[2:3], v[248:249]
	v_pk_add_f32 v[0:1], v[0:1], v[246:247]
	global_store_dwordx4 v[20:21], v[0:3], off offset:576
	s_or_b64 exec, exec, s[26:27]
	s_and_b64 vcc, exec, s[0:1]
	s_mov_b64 s[0:1], -1
	s_cbranch_vccnz .LBB0_886
